# up-proj GEMM K-steps: LDS operand reads renamed into a 16-quad ring and issued 8 reads ahead with counted lgkmcnt (was read->wait(0)->mfma)
# speedup vs baseline: 1.0065x; 1.0065x over previous
; #define SBAR() __builtin_amdgcn_sched_barrier(0)
; DEV void glds16(const u16* g, char* l) { __builtin_amdgcn_global_load_lds((const unsigned*)g, (unsigned*)l, 16, 0, 0); }
; #define GLOAD(kt, buf) do { _Pragma("unroll") for (int i = 0; i < 4; ++i) glds16(Ap + (long)i * 64 * lda + (kt) * 64, As + (buf) * 32768 + soff + i * 8192); \
;     _Pragma("unroll") for (int i = 0; i < NB; ++i) glds16(Bp + (long)i * 64 * ldb + (kt) * 64, Bs + (buf) * 32768 + soff + i * 8192); } while (0)
; template <int WM, int WN, int BN, int EPI>
; DEV void gemm_tile(const u16* __restrict__ A, int lda, const u16* __restrict__ Bt, int ldb, int K, int m0, char* lds,
;                    const Params& P, int layer, int batch, int nt) {
;     ...
;   const int srow = tid >> 3, sch = (tid & 7) ^ ((srow >> 1) & 7);
;   const u16* Ap = A + (long)(m0 + srow) * lda + sch * 8;
;   const u16* Bp = Bt + (long)srow * ldb + sch * 8;
;   const int soff = tid * 16;
;     ...
;   GLOAD(0, 0); asm volatile("s_waitcnt vmcnt(0)" ::: "memory"); __syncthreads();
;   const int nk = K >> 6;
;   for (int kt = 0; kt < nk; ++kt) {
;     const bool more = kt + 1 < nk;
;     const int nb = (kt + 1) & 1;
;     const char* as = As + (kt & 1) * 32768; const char* bs = Bs + (kt & 1) * 32768;
; #pragma unroll
;     for (int ks = 0; ks < 4; ++ks) {
;       if (more) { glds16(Ap + (long)ks * 64 * lda + (kt + 1) * 64, As + nb * 32768 + soff + ks * 8192);
;                   if (ks < NB) glds16(Bp + (long)ks * 64 * ldb + (kt + 1) * 64, Bs + nb * 32768 + soff + ks * 8192); }
;       SBAR();
;       bf16x8 xf[MI], wf[NI];
; #pragma unroll
;       for (int mi = 0; mi < MI; ++mi) xf[mi] = *reinterpret_cast<const bf16x8*>(as + swz128(wm * (MI * 32) + mi * 32 + r32, ks * 2 + hi));
; #pragma unroll
;       for (int ni = 0; ni < NI; ++ni) wf[ni] = *reinterpret_cast<const bf16x8*>(bs + swz128(wn * (NI * 32) + ni * 32 + r32, ks * 2 + hi));
; #pragma unroll
;       for (int mi = 0; mi < MI; ++mi)
; #pragma unroll
;         for (int ni = 0; ni < NI; ++ni) acc[mi][ni] = __builtin_amdgcn_mfma_f32_32x32x16_bf16(wf[ni], xf[mi], acc[mi][ni], 0, 0, 0);
;     }
;     asm volatile("s_waitcnt vmcnt(0)" ::: "memory");
;     __syncthreads();
;   }
.LBB0_358:
	s_mul_i32 s2, s54, 0xc0
	s_mul_i32 s3, s51, 0x300
	s_add_i32 s3, s2, s3
	s_lshl_b32 s3, s3, 9
	s_add_u32 s60, s36, s3
	s_addc_u32 s61, s38, 0
	s_lshl_b32 s3, s55, 8
	v_mov_b32_e32 v100, v226
	s_and_b32 s3, s3, 0x3f00
	s_add_i32 s22, 0, 0x10000
	v_ashrrev_i32_e32 v0, 3, v100
	v_lshrrev_b32_e32 v1, 4, v100
	v_add_u32_e32 v2, s3, v0
	v_xor_b32_e32 v1, v1, v100
	v_ashrrev_i32_e32 v3, 31, v2
	v_lshlrev_b32_e32 v5, 4, v100
	v_lshlrev_b64 v[2:3], 9, v[2:3]
	v_lshlrev_b32_e32 v1, 4, v1
	v_add_u32_e32 v120, 0, v5
	v_lshl_add_u64 v[2:3], s[6:7], 0, v[2:3]
	v_and_b32_e32 v184, 0x70, v1
	v_readfirstlane_b32 s82, v120
	v_add_u32_e32 v6, 0x2000, v120
	v_lshl_add_u64 v[96:97], v[2:3], 0, v[184:185]
	v_ashrrev_i32_e32 v1, 31, v0
	s_mov_b32 m0, s82
	v_readfirstlane_b32 s79, v6
	v_add_u32_e32 v6, 0x4000, v120
	v_lshlrev_b64 v[0:1], 9, v[0:1]
	global_load_lds_dwordx4 v[96:97], off
	v_lshl_add_u64 v[2:3], v[96:97], 0, s[40:41]
	s_mov_b32 m0, s79
	v_readfirstlane_b32 s65, v6
	v_lshl_add_u64 v[0:1], s[60:61], 0, v[0:1]
	global_load_lds_dwordx4 v[2:3], off
	v_lshl_add_u64 v[2:3], v[96:97], 0, s[28:29]
	s_mov_b32 m0, s65
	s_mov_b64 s[60:61], 0x18000
	v_add_u32_e32 v6, 0x6000, v120
	global_load_lds_dwordx4 v[2:3], off
	v_lshl_add_u64 v[2:3], v[96:97], 0, s[60:61]
	v_readfirstlane_b32 s60, v6
	s_mov_b32 m0, s60
	v_add_u32_e32 v121, s22, v5
	global_load_lds_dwordx4 v[2:3], off
	v_readfirstlane_b32 s81, v121
	v_add_u32_e32 v2, 0x2000, v121
	v_lshl_add_u64 v[98:99], v[0:1], 0, v[184:185]
	s_mov_b32 m0, s81
	v_readfirstlane_b32 s75, v2
	v_add_u32_e32 v2, 0x4000, v121
	global_load_lds_dwordx4 v[98:99], off
	v_lshl_add_u64 v[0:1], v[98:99], 0, s[40:41]
	s_mov_b32 m0, s75
	v_readfirstlane_b32 s61, v2
	v_and_b32_e32 v101, 31, v100
	global_load_lds_dwordx4 v[0:1], off
	v_lshl_add_u64 v[0:1], v[98:99], 0, s[28:29]
	s_mov_b32 m0, s61
	v_add_u32_e32 v5, 0x8000, v120
	v_ashrrev_i32_e32 v103, 6, v100
	global_load_lds_dwordx4 v[0:1], off
	v_lshlrev_b32_e32 v1, 7, v101
	v_add_u32_e32 v6, 0x8000, v121
	v_readfirstlane_b32 s62, v5
	v_lshlrev_b32_e32 v0, 12, v103
	v_add_u32_e32 v124, s22, v1
	v_lshl_add_u64 v[2:3], v[96:97], 0, s[30:31]
	s_mov_b32 m0, s62
	v_readfirstlane_b32 s22, v6
	s_waitcnt vmcnt(0)
	s_waitcnt vmcnt(0) lgkmcnt(0)
	s_barrier
	v_add3_u32 v123, 0, v0, v1
	v_lshl_add_u64 v[0:1], v[98:99], 0, s[30:31]
	global_load_lds_dwordx4 v[2:3], off
	s_mov_b32 m0, s22
	v_lshrrev_b32_e32 v4, 5, v100
	global_load_lds_dwordx4 v[0:1], off
	v_bfe_u32 v102, v100, 5, 1
	v_bfe_u32 v122, v100, 1, 3
	v_bitop3_b32 v0, v4, v122, 1 bitop3:0x6c
	v_lshlrev_b32_e32 v4, 4, v0
	v_add_u32_e32 v104, v124, v4
	ds_read_b128 v[194:197], v104
	v_add_u32_e32 v125, v123, v4
	ds_read_b128 v[198:201], v125
	ds_read_b128 v[202:205], v104 offset:4096
	ds_read_b128 v[206:209], v104 offset:8192
	ds_read_b128 v[210:213], v104 offset:12288
	ds_read_b128 v[214:217], v104 offset:16384
	ds_read_b128 v[218:221], v104 offset:20480
	v_add_u32_e32 v26, 0xa000, v121
	v_lshl_add_u64 v[24:25], v[96:97], 0, s[42:43]
	v_readfirstlane_b32 s63, v26
	s_waitcnt lgkmcnt(5)
	v_mfma_f32_32x32x16_bf16 v[80:95], v[194:197], v[198:201], 0
	s_waitcnt lgkmcnt(3)
	v_mfma_f32_32x32x16_bf16 v[64:79], v[202:205], v[198:201], 0
	v_mfma_f32_32x32x16_bf16 v[48:63], v[206:209], v[198:201], 0
	s_waitcnt lgkmcnt(0)
	v_mfma_f32_32x32x16_bf16 v[32:47], v[210:213], v[198:201], 0
	v_add_u32_e32 v0, 0xa000, v120
	s_nop 0
	v_readfirstlane_b32 s74, v0
	s_mov_b32 m0, s74
	s_nop 0
	global_load_lds_dwordx4 v[24:25], off
	v_lshl_add_u64 v[24:25], v[98:99], 0, s[42:43]
	s_mov_b32 m0, s63
	v_mfma_f32_32x32x16_bf16 v[0:15], v[214:217], v[198:201], 0
	global_load_lds_dwordx4 v[24:25], off
	v_mfma_f32_32x32x16_bf16 v[16:31], v[218:221], v[198:201], 0
	v_bitop3_b32 v105, v102, v122, 2 bitop3:0x36
	v_lshlrev_b32_e32 v110, 4, v105
	v_add_u32_e32 v105, v124, v110
	ds_read_b128 v[222:225], v105
	v_add_u32_e32 v126, v123, v110
	ds_read_b128 v[232:235], v126
	ds_read_b128 v[236:239], v105 offset:4096
	ds_read_b128 v[240:243], v105 offset:8192
	ds_read_b128 v[244:247], v105 offset:12288
	ds_read_b128 v[248:251], v105 offset:16384
	ds_read_b128 v[142:145], v105 offset:20480
	v_add_u32_e32 v127, 0xc000, v120
	s_mov_b64 s[86:87], 0x10080
	v_readfirstlane_b32 s78, v127
	v_lshl_add_u64 v[118:119], v[96:97], 0, s[86:87]
	s_mov_b32 m0, s78
	s_waitcnt lgkmcnt(5)
	v_mfma_f32_32x32x16_bf16 v[80:95], v[222:225], v[232:235], v[80:95]
	s_waitcnt lgkmcnt(3)
	v_mfma_f32_32x32x16_bf16 v[64:79], v[236:239], v[232:235], v[64:79]
	v_mfma_f32_32x32x16_bf16 v[48:63], v[240:243], v[232:235], v[48:63]
	s_waitcnt lgkmcnt(1)
	v_mfma_f32_32x32x16_bf16 v[0:15], v[248:251], v[232:235], v[0:15]
	v_add_u32_e32 v116, 0xc000, v121
	v_lshl_add_u64 v[114:115], v[98:99], 0, s[86:87]
	v_readfirstlane_b32 s64, v116
	v_mfma_f32_32x32x16_bf16 v[32:47], v[244:247], v[232:235], v[32:47]
	global_load_lds_dwordx4 v[118:119], off
	s_mov_b32 m0, s64
	s_nop 0
	global_load_lds_dwordx4 v[114:115], off
	s_waitcnt lgkmcnt(0)
	v_mfma_f32_32x32x16_bf16 v[16:31], v[142:145], v[232:235], v[16:31]
	v_bitop3_b32 v106, v102, v122, 4 bitop3:0x36
	v_lshlrev_b32_e32 v110, 4, v106
	v_add_u32_e32 v118, v124, v110
	ds_read_b128 v[146:149], v118
	v_add_u32_e32 v119, v123, v110
	ds_read_b128 v[150:153], v119
	ds_read_b128 v[194:197], v118 offset:4096
	ds_read_b128 v[198:201], v118 offset:8192
	ds_read_b128 v[202:205], v118 offset:12288
	ds_read_b128 v[206:209], v118 offset:16384
	ds_read_b128 v[210:213], v118 offset:20480
	s_mov_b64 s[86:87], 0x18080
	s_waitcnt lgkmcnt(5)
	v_mfma_f32_32x32x16_bf16 v[80:95], v[146:149], v[150:153], v[80:95]
	s_waitcnt lgkmcnt(3)
; #define SBAR() __builtin_amdgcn_sched_barrier(0)
; DEV void glds16(const u16* g, char* l) { __builtin_amdgcn_global_load_lds((const unsigned*)g, (unsigned*)l, 16, 0, 0); }
; template <int WM, int WN, int BN, int EPI>
; DEV void gemm_tile(const u16* __restrict__ A, int lda, const u16* __restrict__ Bt, int ldb, int K, int m0, char* lds,
;                    const Params& P, int layer, int batch, int nt) {
;     ...
;   for (int kt = 0; kt < nk; ++kt) {
;     const bool more = kt + 1 < nk;
;     const int nb = (kt + 1) & 1;
;     const char* as = As + (kt & 1) * 32768; const char* bs = Bs + (kt & 1) * 32768;
; #pragma unroll
;     for (int ks = 0; ks < 4; ++ks) {
;       if (more) { glds16(Ap + (long)ks * 64 * lda + (kt + 1) * 64, As + nb * 32768 + soff + ks * 8192);
;                   if (ks < NB) glds16(Bp + (long)ks * 64 * ldb + (kt + 1) * 64, Bs + nb * 32768 + soff + ks * 8192); }
;       SBAR();
;       bf16x8 xf[MI], wf[NI];
; #pragma unroll
;       for (int mi = 0; mi < MI; ++mi) xf[mi] = *reinterpret_cast<const bf16x8*>(as + swz128(wm * (MI * 32) + mi * 32 + r32, ks * 2 + hi));
; #pragma unroll
;       for (int ni = 0; ni < NI; ++ni) wf[ni] = *reinterpret_cast<const bf16x8*>(bs + swz128(wn * (NI * 32) + ni * 32 + r32, ks * 2 + hi));
; #pragma unroll
;       for (int mi = 0; mi < MI; ++mi)
; #pragma unroll
;         for (int ni = 0; ni < NI; ++ni) acc[mi][ni] = __builtin_amdgcn_mfma_f32_32x32x16_bf16(wf[ni], xf[mi], acc[mi][ni], 0, 0, 0);
;     }
;     asm volatile("s_waitcnt vmcnt(0)" ::: "memory");
;     __syncthreads();
;   }
	v_mfma_f32_32x32x16_bf16 v[64:79], v[194:197], v[150:153], v[64:79]
	v_mfma_f32_32x32x16_bf16 v[48:63], v[198:201], v[150:153], v[48:63]
	s_waitcnt lgkmcnt(1)
	v_mfma_f32_32x32x16_bf16 v[0:15], v[206:209], v[150:153], v[0:15]
	v_add_u32_e32 v116, 0xe000, v120
	v_lshl_add_u64 v[114:115], v[96:97], 0, s[86:87]
	v_readfirstlane_b32 s80, v116
	s_mov_b32 m0, s80
	v_mfma_f32_32x32x16_bf16 v[32:47], v[202:205], v[150:153], v[32:47]
	global_load_lds_dwordx4 v[114:115], off
	s_waitcnt lgkmcnt(0)
	v_mfma_f32_32x32x16_bf16 v[16:31], v[210:213], v[150:153], v[16:31]
	v_bitop3_b32 v106, v102, v122, 6 bitop3:0x36
	v_lshlrev_b32_e32 v110, 4, v106
	v_add_u32_e32 v124, v124, v110
	ds_read_b128 v[214:217], v124
	v_add_u32_e32 v120, v123, v110
	ds_read_b128 v[218:221], v120
	ds_read_b128 v[222:225], v124 offset:4096
	ds_read_b128 v[232:235], v124 offset:8192
	ds_read_b128 v[236:239], v124 offset:12288
	ds_read_b128 v[240:243], v124 offset:16384
	ds_read_b128 v[244:247], v124 offset:20480
	s_mov_b32 m0, s82
	s_mov_b64 s[82:83], 0x100
	s_waitcnt lgkmcnt(5)
	v_mfma_f32_32x32x16_bf16 v[80:95], v[214:217], v[218:221], v[80:95]
	s_waitcnt lgkmcnt(3)
	v_mfma_f32_32x32x16_bf16 v[64:79], v[222:225], v[218:221], v[64:79]
	v_mfma_f32_32x32x16_bf16 v[48:63], v[232:235], v[218:221], v[48:63]
	s_waitcnt lgkmcnt(1)
	v_mfma_f32_32x32x16_bf16 v[0:15], v[240:243], v[218:221], v[0:15]
	v_lshl_add_u64 v[116:117], v[96:97], 0, s[82:83]
	v_lshl_add_u64 v[114:115], v[98:99], 0, s[82:83]
	v_mfma_f32_32x32x16_bf16 v[32:47], v[236:239], v[218:221], v[32:47]
	s_waitcnt vmcnt(0)
	s_waitcnt vmcnt(0) lgkmcnt(0)
	s_barrier
	global_load_lds_dwordx4 v[116:117], off
	s_mov_b32 m0, s81
	v_mfma_f32_32x32x16_bf16 v[16:31], v[244:247], v[218:221], v[16:31]
	global_load_lds_dwordx4 v[114:115], off
	ds_read_b128 v[248:251], v104 offset:32768
	ds_read_b128 v[142:145], v125 offset:32768
	ds_read_b128 v[146:149], v104 offset:36864
	ds_read_b128 v[150:153], v104 offset:40960
	ds_read_b128 v[194:197], v104 offset:45056
	ds_read_b128 v[198:201], v104 offset:49152
	ds_read_b128 v[202:205], v104 offset:53248
	ds_read_b128 v[206:209], v105 offset:32768
	ds_read_b128 v[210:213], v126 offset:32768
	ds_read_b128 v[214:217], v105 offset:36864
	s_mov_b64 s[82:83], 0x8100
	s_mov_b32 m0, s79
	s_waitcnt lgkmcnt(8)
	v_mfma_f32_32x32x16_bf16 v[80:95], v[248:251], v[142:145], v[80:95]
	ds_read_b128 v[218:221], v105 offset:40960
	ds_read_b128 v[222:225], v105 offset:45056
	s_waitcnt lgkmcnt(8)
	v_mfma_f32_32x32x16_bf16 v[64:79], v[146:149], v[142:145], v[64:79]
	v_mfma_f32_32x32x16_bf16 v[48:63], v[150:153], v[142:145], v[48:63]
	ds_read_b128 v[232:235], v105 offset:49152
	ds_read_b128 v[236:239], v105 offset:53248
	s_waitcnt lgkmcnt(8)
	v_mfma_f32_32x32x16_bf16 v[0:15], v[198:201], v[142:145], v[0:15]
	v_lshl_add_u64 v[114:115], v[96:97], 0, s[82:83]
	v_mfma_f32_32x32x16_bf16 v[32:47], v[194:197], v[142:145], v[32:47]
	ds_read_b128 v[240:243], v118 offset:32768
	global_load_lds_dwordx4 v[114:115], off
	v_lshl_add_u64 v[114:115], v[98:99], 0, s[82:83]
	s_mov_b32 m0, s75
	s_nop 0
	global_load_lds_dwordx4 v[114:115], off
	s_waitcnt lgkmcnt(8)
	v_mfma_f32_32x32x16_bf16 v[16:31], v[202:205], v[142:145], v[16:31]
	ds_read_b128 v[244:247], v119 offset:32768
	ds_read_b128 v[248:251], v118 offset:36864
	s_mov_b64 s[82:83], 0x10100
	s_mov_b32 m0, s65
	s_waitcnt lgkmcnt(8)
	v_mfma_f32_32x32x16_bf16 v[80:95], v[206:209], v[210:213], v[80:95]
	ds_read_b128 v[142:145], v118 offset:40960
	ds_read_b128 v[146:149], v118 offset:45056
	s_waitcnt lgkmcnt(8)
	v_mfma_f32_32x32x16_bf16 v[64:79], v[214:217], v[210:213], v[64:79]
	v_mfma_f32_32x32x16_bf16 v[48:63], v[218:221], v[210:213], v[48:63]
	ds_read_b128 v[150:153], v118 offset:49152
	ds_read_b128 v[194:197], v118 offset:53248
	s_waitcnt lgkmcnt(8)
	v_mfma_f32_32x32x16_bf16 v[0:15], v[232:235], v[210:213], v[0:15]
	v_lshl_add_u64 v[114:115], v[96:97], 0, s[82:83]
	v_mfma_f32_32x32x16_bf16 v[32:47], v[222:225], v[210:213], v[32:47]
	ds_read_b128 v[198:201], v124 offset:32768
	global_load_lds_dwordx4 v[114:115], off
	v_lshl_add_u64 v[114:115], v[98:99], 0, s[82:83]
	s_mov_b32 m0, s61
	s_nop 0
	global_load_lds_dwordx4 v[114:115], off
	s_waitcnt lgkmcnt(8)
	v_mfma_f32_32x32x16_bf16 v[16:31], v[236:239], v[210:213], v[16:31]
	ds_read_b128 v[202:205], v120 offset:32768
	ds_read_b128 v[206:209], v124 offset:36864
	s_mov_b32 m0, s60
	s_mov_b64 s[60:61], 0x18100
	s_waitcnt lgkmcnt(8)
	v_mfma_f32_32x32x16_bf16 v[80:95], v[240:243], v[244:247], v[80:95]
	ds_read_b128 v[210:213], v124 offset:40960
	ds_read_b128 v[214:217], v124 offset:45056
	s_waitcnt lgkmcnt(8)
	v_mfma_f32_32x32x16_bf16 v[64:79], v[248:251], v[244:247], v[64:79]
	v_mfma_f32_32x32x16_bf16 v[48:63], v[142:145], v[244:247], v[48:63]
	ds_read_b128 v[218:221], v124 offset:49152
	ds_read_b128 v[222:225], v124 offset:53248
	s_waitcnt lgkmcnt(8)
	v_mfma_f32_32x32x16_bf16 v[0:15], v[150:153], v[244:247], v[0:15]
	v_lshl_add_u64 v[114:115], v[96:97], 0, s[60:61]
	v_mfma_f32_32x32x16_bf16 v[32:47], v[146:149], v[244:247], v[32:47]
	global_load_lds_dwordx4 v[114:115], off
	s_waitcnt lgkmcnt(7)
	v_mfma_f32_32x32x16_bf16 v[16:31], v[194:197], v[244:247], v[16:31]
	s_mov_b64 s[60:61], 0x180
	s_mov_b32 m0, s62
	s_waitcnt lgkmcnt(5)
	v_mfma_f32_32x32x16_bf16 v[80:95], v[198:201], v[202:205], v[80:95]
	s_waitcnt lgkmcnt(3)
	v_mfma_f32_32x32x16_bf16 v[64:79], v[206:209], v[202:205], v[64:79]
	v_mfma_f32_32x32x16_bf16 v[48:63], v[210:213], v[202:205], v[48:63]
	s_waitcnt lgkmcnt(1)
	v_mfma_f32_32x32x16_bf16 v[0:15], v[218:221], v[202:205], v[0:15]
	v_lshl_add_u64 v[116:117], v[96:97], 0, s[60:61]
	v_lshl_add_u64 v[114:115], v[98:99], 0, s[60:61]
	v_mfma_f32_32x32x16_bf16 v[32:47], v[214:217], v[202:205], v[32:47]
	s_waitcnt vmcnt(0)
	s_waitcnt vmcnt(0) lgkmcnt(0)
	s_barrier
; #define SBAR() __builtin_amdgcn_sched_barrier(0)
; DEV void glds16(const u16* g, char* l) { __builtin_amdgcn_global_load_lds((const unsigned*)g, (unsigned*)l, 16, 0, 0); }
; template <int WM, int WN, int BN, int EPI>
; DEV void gemm_tile(const u16* __restrict__ A, int lda, const u16* __restrict__ Bt, int ldb, int K, int m0, char* lds,
;                    const Params& P, int layer, int batch, int nt) {
;     ...
;   for (int kt = 0; kt < nk; ++kt) {
;     const bool more = kt + 1 < nk;
;     const int nb = (kt + 1) & 1;
;     const char* as = As + (kt & 1) * 32768; const char* bs = Bs + (kt & 1) * 32768;
; #pragma unroll
;     for (int ks = 0; ks < 4; ++ks) {
;       if (more) { glds16(Ap + (long)ks * 64 * lda + (kt + 1) * 64, As + nb * 32768 + soff + ks * 8192);
;                   if (ks < NB) glds16(Bp + (long)ks * 64 * ldb + (kt + 1) * 64, Bs + nb * 32768 + soff + ks * 8192); }
;       SBAR();
;       bf16x8 xf[MI], wf[NI];
; #pragma unroll
;       for (int mi = 0; mi < MI; ++mi) xf[mi] = *reinterpret_cast<const bf16x8*>(as + swz128(wm * (MI * 32) + mi * 32 + r32, ks * 2 + hi));
; #pragma unroll
;       for (int ni = 0; ni < NI; ++ni) wf[ni] = *reinterpret_cast<const bf16x8*>(bs + swz128(wn * (NI * 32) + ni * 32 + r32, ks * 2 + hi));
; #pragma unroll
;       for (int mi = 0; mi < MI; ++mi)
; #pragma unroll
;         for (int ni = 0; ni < NI; ++ni) acc[mi][ni] = __builtin_amdgcn_mfma_f32_32x32x16_bf16(wf[ni], xf[mi], acc[mi][ni], 0, 0, 0);
;     }
;     asm volatile("s_waitcnt vmcnt(0)" ::: "memory");
;     __syncthreads();
;   }
	global_load_lds_dwordx4 v[116:117], off
	s_mov_b32 m0, s22
	v_mfma_f32_32x32x16_bf16 v[16:31], v[222:225], v[202:205], v[16:31]
	global_load_lds_dwordx4 v[114:115], off
	ds_read_b128 v[232:235], v104
	ds_read_b128 v[236:239], v125
	ds_read_b128 v[240:243], v104 offset:4096
	ds_read_b128 v[244:247], v104 offset:8192
	ds_read_b128 v[248:251], v104 offset:12288
	ds_read_b128 v[142:145], v104 offset:16384
	ds_read_b128 v[146:149], v104 offset:20480
	ds_read_b128 v[150:153], v105
	ds_read_b128 v[194:197], v126
	ds_read_b128 v[198:201], v105 offset:4096
	s_mov_b64 s[60:61], 0x8180
	s_mov_b32 m0, s74
	s_waitcnt lgkmcnt(8)
	v_mfma_f32_32x32x16_bf16 v[80:95], v[232:235], v[236:239], v[80:95]
	ds_read_b128 v[202:205], v105 offset:8192
	ds_read_b128 v[206:209], v105 offset:12288
	s_waitcnt lgkmcnt(8)
	v_mfma_f32_32x32x16_bf16 v[64:79], v[240:243], v[236:239], v[64:79]
	v_mfma_f32_32x32x16_bf16 v[48:63], v[244:247], v[236:239], v[48:63]
	ds_read_b128 v[210:213], v105 offset:16384
	ds_read_b128 v[214:217], v105 offset:20480
	s_waitcnt lgkmcnt(8)
	v_mfma_f32_32x32x16_bf16 v[0:15], v[142:145], v[236:239], v[0:15]
	v_lshl_add_u64 v[114:115], v[96:97], 0, s[60:61]
	v_mfma_f32_32x32x16_bf16 v[32:47], v[248:251], v[236:239], v[32:47]
	ds_read_b128 v[218:221], v118
	global_load_lds_dwordx4 v[114:115], off
	v_lshl_add_u64 v[114:115], v[98:99], 0, s[60:61]
	s_mov_b32 m0, s63
	s_nop 0
	global_load_lds_dwordx4 v[114:115], off
	s_waitcnt lgkmcnt(8)
	v_mfma_f32_32x32x16_bf16 v[16:31], v[146:149], v[236:239], v[16:31]
	ds_read_b128 v[222:225], v119
	ds_read_b128 v[232:235], v118 offset:4096
	s_mov_b64 s[60:61], 0x10180
	s_mov_b32 m0, s78
	v_lshl_add_u64 v[98:99], v[98:99], 0, s[60:61]
	s_waitcnt lgkmcnt(8)
	v_mfma_f32_32x32x16_bf16 v[80:95], v[150:153], v[194:197], v[80:95]
	ds_read_b128 v[236:239], v118 offset:8192
	ds_read_b128 v[240:243], v118 offset:12288
	s_waitcnt lgkmcnt(8)
	v_mfma_f32_32x32x16_bf16 v[64:79], v[198:201], v[194:197], v[64:79]
	v_mfma_f32_32x32x16_bf16 v[48:63], v[202:205], v[194:197], v[48:63]
	ds_read_b128 v[244:247], v118 offset:16384
	ds_read_b128 v[248:251], v118 offset:20480
	s_waitcnt lgkmcnt(8)
	v_mfma_f32_32x32x16_bf16 v[0:15], v[210:213], v[194:197], v[0:15]
	v_lshl_add_u64 v[114:115], v[96:97], 0, s[60:61]
	v_mfma_f32_32x32x16_bf16 v[32:47], v[206:209], v[194:197], v[32:47]
	ds_read_b128 v[142:145], v124
	global_load_lds_dwordx4 v[114:115], off
	s_mov_b32 m0, s64
	s_nop 0
	global_load_lds_dwordx4 v[98:99], off
	s_waitcnt lgkmcnt(8)
	v_mfma_f32_32x32x16_bf16 v[16:31], v[214:217], v[194:197], v[16:31]
	ds_read_b128 v[146:149], v120
	ds_read_b128 v[150:153], v124 offset:4096
	s_mov_b64 s[60:61], 0x18180
	s_mov_b32 m0, s80
	v_lshl_add_u64 v[96:97], v[96:97], 0, s[60:61]
	s_waitcnt lgkmcnt(8)
	v_mfma_f32_32x32x16_bf16 v[80:95], v[218:221], v[222:225], v[80:95]
	ds_read_b128 v[194:197], v124 offset:8192
	ds_read_b128 v[198:201], v124 offset:12288
	s_waitcnt lgkmcnt(8)
	v_mfma_f32_32x32x16_bf16 v[64:79], v[232:235], v[222:225], v[64:79]
	v_mfma_f32_32x32x16_bf16 v[48:63], v[236:239], v[222:225], v[48:63]
	ds_read_b128 v[202:205], v124 offset:16384
	ds_read_b128 v[206:209], v124 offset:20480
	s_waitcnt lgkmcnt(8)
	v_mfma_f32_32x32x16_bf16 v[32:47], v[240:243], v[222:225], v[32:47]
	global_load_lds_dwordx4 v[96:97], off
	v_mfma_f32_32x32x16_bf16 v[0:15], v[244:247], v[222:225], v[0:15]
	s_waitcnt lgkmcnt(7)
	v_mfma_f32_32x32x16_bf16 v[16:31], v[248:251], v[222:225], v[16:31]
	s_waitcnt lgkmcnt(5)
	v_mfma_f32_32x32x16_bf16 v[80:95], v[142:145], v[146:149], v[80:95]
	s_waitcnt lgkmcnt(4)
	v_mfma_f32_32x32x16_bf16 v[64:79], v[150:153], v[146:149], v[64:79]
	s_waitcnt lgkmcnt(3)
	v_mfma_f32_32x32x16_bf16 v[48:63], v[194:197], v[146:149], v[48:63]
	s_waitcnt lgkmcnt(2)
	v_mfma_f32_32x32x16_bf16 v[32:47], v[198:201], v[146:149], v[32:47]
	s_waitcnt lgkmcnt(1)
	v_mfma_f32_32x32x16_bf16 v[0:15], v[202:205], v[146:149], v[0:15]
	s_waitcnt vmcnt(0)
	s_waitcnt vmcnt(0) lgkmcnt(0)
	s_barrier
	v_mfma_f32_32x32x16_bf16 v[16:31], v[206:209], v[146:149], v[16:31]
	ds_read_b128 v[210:213], v104 offset:32768
	ds_read_b128 v[214:217], v125 offset:32768
	ds_read_b128 v[218:221], v104 offset:36864
	ds_read_b128 v[222:225], v104 offset:40960
	ds_read_b128 v[232:235], v104 offset:45056
	ds_read_b128 v[236:239], v104 offset:49152
	ds_read_b128 v[240:243], v104 offset:53248
	ds_read_b128 v[244:247], v105 offset:32768
	ds_read_b128 v[248:251], v126 offset:32768
	ds_read_b128 v[142:145], v105 offset:36864
	s_waitcnt lgkmcnt(8)
	v_mfma_f32_32x32x16_bf16 v[80:95], v[210:213], v[214:217], v[80:95]
	ds_read_b128 v[146:149], v105 offset:40960
	s_waitcnt lgkmcnt(8)
	v_mfma_f32_32x32x16_bf16 v[64:79], v[218:221], v[214:217], v[64:79]
	ds_read_b128 v[150:153], v105 offset:45056
	s_waitcnt lgkmcnt(8)
	v_mfma_f32_32x32x16_bf16 v[48:63], v[222:225], v[214:217], v[48:63]
	ds_read_b128 v[194:197], v105 offset:49152
	s_waitcnt lgkmcnt(8)
	v_mfma_f32_32x32x16_bf16 v[32:47], v[232:235], v[214:217], v[32:47]
	ds_read_b128 v[198:201], v105 offset:53248
	s_waitcnt lgkmcnt(8)
	v_mfma_f32_32x32x16_bf16 v[0:15], v[236:239], v[214:217], v[0:15]
	ds_read_b128 v[202:205], v118 offset:32768
	s_waitcnt lgkmcnt(8)
	v_mfma_f32_32x32x16_bf16 v[16:31], v[240:243], v[214:217], v[16:31]
	ds_read_b128 v[206:209], v119 offset:32768
	ds_read_b128 v[210:213], v118 offset:36864
	s_waitcnt lgkmcnt(8)
	v_mfma_f32_32x32x16_bf16 v[80:95], v[244:247], v[248:251], v[80:95]
	ds_read_b128 v[214:217], v118 offset:40960
	s_waitcnt lgkmcnt(8)
	v_mfma_f32_32x32x16_bf16 v[64:79], v[142:145], v[248:251], v[64:79]
	ds_read_b128 v[218:221], v118 offset:45056
	s_waitcnt lgkmcnt(8)
; #define SBAR() __builtin_amdgcn_sched_barrier(0)
; DEV void glds16(const u16* g, char* l) { __builtin_amdgcn_global_load_lds((const unsigned*)g, (unsigned*)l, 16, 0, 0); }
; DEV void epi_uq(f32x16 (&acc)[1][6], const Params& P, int layer, int batch, int m0, int head, int wid, int r32, int hi, char* lds) {
;   const int t = m0 + wid * 32 + r32;
;   const float rc = __builtin_amdgcn_rsqf((WS{P.ws}.ssq_cq()[t] + WS{P.ws}.ssq_cq()[TB + t] + WS{P.ws}.ssq_cq()[2 * TB + t] + WS{P.ws}.ssq_cq()[3 * TB + t]) * (1.f / 256.f) + EPS);
;   float s = 0.f;
; #pragma unroll
;   for (int ni = 0; ni < 6; ++ni)
; #pragma unroll
;     for (int r = 0; r < 16; ++r) { acc[0][ni][r] *= rc; s += acc[0][ni][r] * acc[0][ni][r]; }
; template <int WM, int WN, int BN, int EPI>
; DEV void gemm_tile(const u16* __restrict__ A, int lda, const u16* __restrict__ Bt, int ldb, int K, int m0, char* lds,
;                    const Params& P, int layer, int batch, int nt) {
;     ...
;   for (int kt = 0; kt < nk; ++kt) {
;     const bool more = kt + 1 < nk;
;     const int nb = (kt + 1) & 1;
;     const char* as = As + (kt & 1) * 32768; const char* bs = Bs + (kt & 1) * 32768;
; #pragma unroll
;     for (int ks = 0; ks < 4; ++ks) {
;       if (more) { glds16(Ap + (long)ks * 64 * lda + (kt + 1) * 64, As + nb * 32768 + soff + ks * 8192);
;                   if (ks < NB) glds16(Bp + (long)ks * 64 * ldb + (kt + 1) * 64, Bs + nb * 32768 + soff + ks * 8192); }
;       SBAR();
;       bf16x8 xf[MI], wf[NI];
; #pragma unroll
;       for (int mi = 0; mi < MI; ++mi) xf[mi] = *reinterpret_cast<const bf16x8*>(as + swz128(wm * (MI * 32) + mi * 32 + r32, ks * 2 + hi));
; #pragma unroll
;       for (int ni = 0; ni < NI; ++ni) wf[ni] = *reinterpret_cast<const bf16x8*>(bs + swz128(wn * (NI * 32) + ni * 32 + r32, ks * 2 + hi));
; #pragma unroll
;       for (int mi = 0; mi < MI; ++mi)
; #pragma unroll
;         for (int ni = 0; ni < NI; ++ni) acc[mi][ni] = __builtin_amdgcn_mfma_f32_32x32x16_bf16(wf[ni], xf[mi], acc[mi][ni], 0, 0, 0);
;     }
;     asm volatile("s_waitcnt vmcnt(0)" ::: "memory");
;     __syncthreads();
;   }
	v_mfma_f32_32x32x16_bf16 v[48:63], v[146:149], v[248:251], v[48:63]
	ds_read_b128 v[222:225], v118 offset:49152
	s_waitcnt lgkmcnt(8)
	v_mfma_f32_32x32x16_bf16 v[32:47], v[150:153], v[248:251], v[32:47]
	ds_read_b128 v[232:235], v118 offset:53248
	s_waitcnt lgkmcnt(8)
	v_mfma_f32_32x32x16_bf16 v[0:15], v[194:197], v[248:251], v[0:15]
	s_waitcnt lgkmcnt(7)
	v_mfma_f32_32x32x16_bf16 v[16:31], v[198:201], v[248:251], v[16:31]
	s_waitcnt lgkmcnt(5)
	v_mfma_f32_32x32x16_bf16 v[80:95], v[202:205], v[206:209], v[80:95]
	s_waitcnt lgkmcnt(4)
	v_mfma_f32_32x32x16_bf16 v[64:79], v[210:213], v[206:209], v[64:79]
	s_waitcnt lgkmcnt(3)
	v_mfma_f32_32x32x16_bf16 v[48:63], v[214:217], v[206:209], v[48:63]
	s_waitcnt lgkmcnt(2)
	v_mfma_f32_32x32x16_bf16 v[32:47], v[218:221], v[206:209], v[32:47]
	s_waitcnt lgkmcnt(1)
	v_mfma_f32_32x32x16_bf16 v[0:15], v[222:225], v[206:209], v[0:15]
	s_waitcnt lgkmcnt(0)
	v_mfma_f32_32x32x16_bf16 v[16:31], v[232:235], v[206:209], v[16:31]
	ds_read_b128 v[96:99], v124 offset:32768
	ds_read_b128 v[104:107], v120 offset:32768
	ds_read_b128 v[108:111], v124 offset:36864
	ds_read_b128 v[112:115], v124 offset:40960
	ds_read_b128 v[116:119], v124 offset:45056
	ds_read_b128 v[120:123], v124 offset:49152
	ds_read_b128 v[124:127], v124 offset:53248
	s_waitcnt vmcnt(0)
	s_waitcnt lgkmcnt(5)
	v_mfma_f32_32x32x16_bf16 v[80:95], v[96:99], v[104:107], v[80:95]
	v_lshl_add_u32 v99, v103, 5, s3
	v_or_b32_e32 v96, v99, v101
	v_ashrrev_i32_e32 v97, 31, v96
	s_mov_b32 s3, 0x20000
	s_waitcnt lgkmcnt(0)
	s_barrier
	v_mfma_f32_32x32x16_bf16 v[64:79], v[108:111], v[104:107], v[64:79]
	v_lshl_add_u64 v[108:109], v[96:97], 2, s[8:9]
	v_add_co_u32_e32 v110, vcc, s93, v108
	v_lshlrev_b32_e32 v184, 4, v102
	s_nop 0
	v_addc_co_u32_e32 v111, vcc, 0, v109, vcc
	s_lshl_b32 s22, s2, 1
	v_mfma_f32_32x32x16_bf16 v[48:63], v[112:115], v[104:107], v[48:63]
	v_add_co_u32_e32 v112, vcc, s3, v108
	s_mov_b32 s3, 0x30000
	s_nop 0
	v_addc_co_u32_e32 v113, vcc, 0, v109, vcc
	v_add_co_u32_e32 v114, vcc, s3, v108
	v_mfma_f32_32x32x16_bf16 v[32:47], v[116:119], v[104:107], v[32:47]
	s_nop 0
	v_addc_co_u32_e32 v115, vcc, 0, v109, vcc
	flat_load_dword v97, v[108:109]
	flat_load_dword v98, v[110:111]
	s_nop 0
	flat_load_dword v108, v[112:113]
	flat_load_dword v109, v[114:115]
	s_movk_i32 s3, 0xfff
	s_waitcnt vmcnt(0) lgkmcnt(0)
	v_add_f32_e32 v97, v97, v98
	v_add_f32_e32 v97, v97, v108
	v_add_f32_e32 v97, v97, v109
	v_fmamk_f32 v97, v97, 0x3b800000, v227
	v_rsq_f32_e32 v98, v97
	v_mfma_f32_32x32x16_bf16 v[0:15], v[120:123], v[104:107], v[0:15]
	v_mul_f32_e32 v108, v81, v98
	v_mul_f32_e32 v97, v80, v98
	v_mul_f32_e32 v113, v86, v98
	v_mul_f32_e32 v86, v108, v108
	v_mul_f32_e32 v109, v82, v98
	v_fmac_f32_e32 v86, v97, v97
	v_mul_f32_e32 v110, v83, v98
	v_fmac_f32_e32 v86, v109, v109
	v_mul_f32_e32 v111, v84, v98
	v_fmac_f32_e32 v86, v110, v110
	v_mul_f32_e32 v112, v85, v98
	v_fmac_f32_e32 v86, v111, v111
	v_fmac_f32_e32 v86, v112, v112
	v_mul_f32_e32 v114, v87, v98
	v_fmac_f32_e32 v86, v113, v113
	v_mul_f32_e32 v115, v88, v98
	v_fmac_f32_e32 v86, v114, v114
	v_mul_f32_e32 v116, v89, v98
	v_fmac_f32_e32 v86, v115, v115
	v_mul_f32_e32 v117, v90, v98
	v_fmac_f32_e32 v86, v116, v116
	v_mul_f32_e32 v118, v91, v98
	v_fmac_f32_e32 v86, v117, v117
	v_mul_f32_e32 v119, v92, v98
	v_fmac_f32_e32 v86, v118, v118
	v_mul_f32_e32 v120, v93, v98
	v_fmac_f32_e32 v86, v119, v119
	v_mul_f32_e32 v121, v94, v98
	v_fmac_f32_e32 v86, v120, v120
	v_mul_f32_e32 v122, v95, v98
	v_fmac_f32_e32 v86, v121, v121
	v_mul_f32_e32 v123, v64, v98
	v_fmac_f32_e32 v86, v122, v122
	v_mfma_f32_32x32x16_bf16 v[16:31], v[124:127], v[104:107], v[16:31]
	v_mul_f32_e32 v124, v65, v98
	v_fmac_f32_e32 v86, v123, v123
	v_mul_f32_e32 v125, v66, v98
	v_fmac_f32_e32 v86, v124, v124
	v_mul_f32_e32 v126, v67, v98
	v_fmac_f32_e32 v86, v125, v125
	v_mul_f32_e32 v127, v68, v98
	v_fmac_f32_e32 v86, v126, v126
	v_mul_f32_e32 v128, v69, v98
	v_fmac_f32_e32 v86, v127, v127
	v_mul_f32_e32 v129, v70, v98
	v_fmac_f32_e32 v86, v128, v128
	v_mul_f32_e32 v130, v71, v98
	v_fmac_f32_e32 v86, v129, v129
	v_mul_f32_e32 v80, v72, v98
	v_fmac_f32_e32 v86, v130, v130
	v_mul_f32_e32 v81, v73, v98
	v_fmac_f32_e32 v86, v80, v80
	v_mul_f32_e32 v82, v74, v98
	v_fmac_f32_e32 v86, v81, v81
	v_mul_f32_e32 v83, v75, v98
	v_fmac_f32_e32 v86, v82, v82
	v_mul_f32_e32 v72, v76, v98
	v_fmac_f32_e32 v86, v83, v83
	v_mul_f32_e32 v73, v77, v98
	v_fmac_f32_e32 v86, v72, v72
	v_mul_f32_e32 v74, v78, v98
	v_fmac_f32_e32 v86, v73, v73
	v_mul_f32_e32 v75, v79, v98
	v_fmac_f32_e32 v86, v74, v74
	v_mul_f32_e32 v131, v36, v98
	v_mul_f32_e32 v132, v37, v98
	v_lshl_add_u64 v[36:37], s[10:11], 0, v[184:185]
	v_mul_f32_e32 v68, v48, v98
	v_mul_f32_e32 v70, v50, v98
	v_mul_f32_e32 v71, v51, v98
	v_mul_f32_e32 v66, v54, v98
	v_mul_f32_e32 v67, v55, v98
	v_mul_f32_e32 v54, v56, v98
	v_mul_f32_e32 v55, v57, v98
	v_mul_f32_e32 v56, v58, v98
	v_mul_f32_e32 v57, v59, v98
	v_mul_f32_e32 v50, v60, v98
	v_mul_f32_e32 v51, v61, v98
	v_fmac_f32_e32 v86, v75, v75
	flat_load_dwordx4 v[58:61], v[36:37] offset:1280
	global_load_dwordx4 v[194:197], v[36:37], off offset:1312
	global_load_dwordx4 v[198:201], v[36:37], off offset:1344
	global_load_dwordx4 v[202:205], v[36:37], off offset:1376
	global_load_dwordx4 v[206:209], v[36:37], off offset:1408
	global_load_dwordx4 v[210:213], v[36:37], off offset:1440
	global_load_dwordx4 v[214:217], v[36:37], off offset:1472
	global_load_dwordx4 v[218:221], v[36:37], off offset:1504
	global_load_dwordx4 v[222:225], v[36:37], off offset:1536
	global_load_dwordx4 v[232:235], v[36:37], off offset:1568
	global_load_dwordx4 v[236:239], v[36:37], off offset:1600
; DEV void epi_uq(f32x16 (&acc)[1][6], const Params& P, int layer, int batch, int m0, int head, int wid, int r32, int hi, char* lds) {
;   const int t = m0 + wid * 32 + r32;
;   const float rc = __builtin_amdgcn_rsqf((WS{P.ws}.ssq_cq()[t] + WS{P.ws}.ssq_cq()[TB + t] + WS{P.ws}.ssq_cq()[2 * TB + t] + WS{P.ws}.ssq_cq()[3 * TB + t]) * (1.f / 256.f) + EPS);
;   float s = 0.f;
; #pragma unroll
;   for (int ni = 0; ni < 6; ++ni)
; #pragma unroll
;     for (int r = 0; r < 16; ++r) { acc[0][ni][r] *= rc; s += acc[0][ni][r] * acc[0][ni][r]; }
;   s = swapsum(s);
;   constexpr float SCQ = 0.07216878364870323f * LOG2E;
;   const float inv = __builtin_amdgcn_rsqf(s * (1.f / 192.f) + EPS) * SCQ;
;   const float* g = WS{P.ws}.consts() + layer * 1024 + 320;
;   char* slab = lds + wid * 12800; char* dst = slab + r32 * 400;
	global_load_dwordx4 v[240:243], v[36:37], off offset:1632
	global_load_dwordx4 v[244:247], v[36:37], off offset:1664
	global_load_dwordx4 v[248:251], v[36:37], off offset:1696
	global_load_dwordx4 v[170:173], v[36:37], off offset:1728
	global_load_dwordx4 v[174:177], v[36:37], off offset:1760
	v_mul_f32_e32 v69, v49, v98
	v_fmac_f32_e32 v86, v68, v68
	v_fmac_f32_e32 v86, v69, v69
	v_fmac_f32_e32 v86, v70, v70
	v_mul_f32_e32 v64, v52, v98
	v_fmac_f32_e32 v86, v71, v71
	v_mul_f32_e32 v65, v53, v98
	v_fmac_f32_e32 v86, v64, v64
	v_fmac_f32_e32 v86, v65, v65
	v_fmac_f32_e32 v86, v66, v66
	v_fmac_f32_e32 v86, v67, v67
	v_fmac_f32_e32 v86, v54, v54
	v_fmac_f32_e32 v86, v55, v55
	v_fmac_f32_e32 v86, v56, v56
	v_fmac_f32_e32 v86, v57, v57
	v_fmac_f32_e32 v86, v50, v50
	v_mul_f32_e32 v52, v62, v98
	v_fmac_f32_e32 v86, v51, v51
	v_mul_f32_e32 v53, v63, v98
	v_fmac_f32_e32 v86, v52, v52
	v_mul_f32_e32 v48, v32, v98
	v_fmac_f32_e32 v86, v53, v53
	v_mul_f32_e32 v33, v33, v98
	v_fmac_f32_e32 v86, v48, v48
	v_mul_f32_e32 v49, v34, v98
	v_fmac_f32_e32 v86, v33, v33
	v_mul_f32_e32 v35, v35, v98
	v_fmac_f32_e32 v86, v49, v49
	v_fmac_f32_e32 v86, v35, v35
	v_fmac_f32_e32 v86, v131, v131
	v_fmac_f32_e32 v86, v132, v132
	v_mul_f32_e32 v133, v38, v98
	v_fmac_f32_e32 v86, v133, v133
	v_mul_f32_e32 v134, v39, v98
	v_fmac_f32_e32 v86, v134, v134
	v_mul_f32_e32 v135, v40, v98
	v_fmac_f32_e32 v86, v135, v135
	v_mul_f32_e32 v136, v41, v98
	v_fmac_f32_e32 v86, v136, v136
	v_mul_f32_e32 v137, v42, v98
	v_fmac_f32_e32 v86, v137, v137
	v_mul_f32_e32 v138, v43, v98
	v_fmac_f32_e32 v86, v138, v138
	v_mul_f32_e32 v139, v44, v98
	v_fmac_f32_e32 v86, v139, v139
	v_mul_f32_e32 v140, v45, v98
	v_mul_f32_e32 v34, v14, v98
	v_mul_lo_u32 v14, v103, s99
	v_fmac_f32_e32 v86, v140, v140
	v_mul_f32_e32 v141, v46, v98
	v_mul_f32_e32 v32, v15, v98
	v_add_u32_e32 v46, 0, v14
	v_mov_b32_e32 v14, v2
	v_mov_b32_e32 v15, v18
	v_mov_b32_e32 v18, v3
	v_mov_b32_e32 v2, v0
	v_mov_b32_e32 v3, v16
	v_fmac_f32_e32 v86, v141, v141
	v_mul_f32_e32 v47, v47, v98
	v_pk_mul_f32 v[42:43], v[2:3], v[98:99] op_sel_hi:[1,0]
	v_mov_b32_e32 v16, v1
	v_fmac_f32_e32 v86, v47, v47
	v_pk_mul_f32 v[84:85], v[42:43], v[42:43]
	v_pk_mul_f32 v[44:45], v[16:17], v[98:99] op_sel_hi:[1,0]
	v_pk_mul_f32 v[14:15], v[14:15], v[98:99] op_sel_hi:[1,0]
	v_add_f32_e32 v0, v84, v86
	v_pk_mul_f32 v[86:87], v[44:45], v[44:45]
	v_pk_mul_f32 v[76:77], v[14:15], v[14:15]
	v_pk_mul_f32 v[40:41], v[18:19], v[98:99] op_sel_hi:[1,0]
	v_add_f32_e32 v0, v86, v0
	v_pk_mul_f32 v[78:79], v[40:41], v[40:41]
	v_add_f32_e32 v0, v76, v0
	v_add_f32_e32 v16, v78, v0
	v_mov_b32_e32 v0, v6
	v_mov_b32_e32 v1, v22
	v_mov_b32_e32 v22, v7
	v_mov_b32_e32 v6, v4
	v_mov_b32_e32 v7, v20
	v_pk_mul_f32 v[6:7], v[6:7], v[98:99] op_sel_hi:[1,0]
	v_mov_b32_e32 v20, v5
	v_pk_mul_f32 v[92:93], v[6:7], v[6:7]
	v_pk_mul_f32 v[4:5], v[20:21], v[98:99] op_sel_hi:[1,0]
	v_pk_mul_f32 v[0:1], v[0:1], v[98:99] op_sel_hi:[1,0]
	v_add_f32_e32 v16, v92, v16
	v_pk_mul_f32 v[20:21], v[4:5], v[4:5]
	v_pk_mul_f32 v[88:89], v[0:1], v[0:1]
	v_pk_mul_f32 v[2:3], v[22:23], v[98:99] op_sel_hi:[1,0]
	v_add_f32_e32 v16, v20, v16
	v_pk_mul_f32 v[90:91], v[2:3], v[2:3]
	v_add_f32_e32 v16, v88, v16
	v_add_f32_e32 v18, v90, v16
	v_mov_b32_e32 v16, v10
	v_mov_b32_e32 v17, v26
	v_pk_mul_f32 v[22:23], v[16:17], v[98:99] op_sel_hi:[1,0]
	v_mov_b32_e32 v16, v8
	v_mov_b32_e32 v17, v24
	v_pk_mul_f32 v[38:39], v[16:17], v[98:99] op_sel_hi:[1,0]
	v_mov_b32_e32 v24, v9
	v_pk_mul_f32 v[104:105], v[38:39], v[38:39]
	v_pk_mul_f32 v[24:25], v[24:25], v[98:99] op_sel_hi:[1,0]
	v_mov_b32_e32 v26, v11
	v_add_f32_e32 v16, v104, v18
	v_pk_mul_f32 v[8:9], v[24:25], v[24:25]
	v_pk_mul_f32 v[94:95], v[22:23], v[22:23]
	v_pk_mul_f32 v[26:27], v[26:27], v[98:99] op_sel_hi:[1,0]
	v_add_f32_e32 v8, v8, v16
	v_mov_b32_e32 v16, v12
	v_mov_b32_e32 v17, v28
	v_pk_mul_f32 v[10:11], v[26:27], v[26:27]
	v_add_f32_e32 v8, v94, v8
	v_pk_mul_f32 v[16:17], v[16:17], v[98:99] op_sel_hi:[1,0]
	v_mov_b32_e32 v28, v13
	v_add_f32_e32 v8, v10, v8
	v_pk_mul_f32 v[106:107], v[16:17], v[16:17]
	v_pk_mul_f32 v[18:19], v[28:29], v[98:99] op_sel_hi:[1,0]
	v_add_f32_e32 v8, v106, v8
	v_pk_mul_f32 v[12:13], v[18:19], v[18:19]
	v_pk_mul_f32 v[30:31], v[30:31], v[98:99] op_sel_hi:[1,0]
	v_add_f32_e32 v8, v12, v8
	v_fmac_f32_e32 v8, v34, v34
	v_fmac_f32_e32 v8, v32, v32
	v_add_f32_e32 v8, v85, v8
	v_add_f32_e32 v8, v87, v8
	v_add_f32_e32 v8, v77, v8
	v_add_f32_e32 v8, v79, v8
	v_add_f32_e32 v8, v93, v8
	v_add_f32_e32 v8, v21, v8
	v_add_f32_e32 v8, v89, v8
	v_add_f32_e32 v8, v91, v8
	v_add_f32_e32 v8, v105, v8
	v_add_f32_e32 v8, v9, v8
	v_add_f32_e32 v8, v95, v8
	v_add_f32_e32 v8, v11, v8
	v_add_f32_e32 v8, v107, v8
	v_pk_mul_f32 v[62:63], v[30:31], v[30:31]
	v_add_f32_e32 v8, v13, v8
	v_add_f32_e32 v8, v62, v8
	v_add_f32_e32 v8, v63, v8
	v_mov_b32_e32 v9, v8
	s_nop 1
	v_permlane32_swap_b32_e32 v8, v9
	v_add_f32_e32 v8, v8, v9
	v_fmamk_f32 v8, v8, 0x3baaaaab, v227
	v_rsq_f32_e32 v8, v8
	v_mul_u32_u24_e32 v9, 0x190, v101
	v_lshlrev_b32_e32 v10, 3, v102
	v_add3_u32 v21, v46, v9, v10
	v_mul_f32_e32 v20, 0x3dd53b94, v8
	v_mul_f32_e32 v8, v97, v20
	v_mul_f32_e32 v9, v108, v20
	s_waitcnt vmcnt(0) lgkmcnt(0)
; DEV void epi_uq(f32x16 (&acc)[1][6], const Params& P, int layer, int batch, int m0, int head, int wid, int r32, int hi, char* lds) {
;     ...
;   const float inv = __builtin_amdgcn_rsqf(s * (1.f / 192.f) + EPS) * SCQ;
;   const float* g = WS{P.ws}.consts() + layer * 1024 + 320;
;   char* slab = lds + wid * 12800; char* dst = slab + r32 * 400;
; #pragma unroll
;   for (int ni = 0; ni < 4; ++ni)
; #pragma unroll
;     for (int r4 = 0; r4 < 4; ++r4) {
;       const int c = ni * 32 + r4 * 8 + hi * 4;
;       const float4 gg = *reinterpret_cast<const float4*>(g + c);
;       const f32x16& a = acc[0][ni];
;       st4lds(dst, c, a[r4 * 4] * inv * gg.x, a[r4 * 4 + 1] * inv * gg.y, a[r4 * 4 + 2] * inv * gg.z, a[r4 * 4 + 3] * inv * gg.w);
;     }
	v_mul_f32_e32 v8, v58, v8
	v_mul_f32_e32 v9, v59, v9
	v_mul_f32_e32 v10, v109, v20
	v_mul_f32_e32 v11, v110, v20
	v_mul_f32_e32 v10, v60, v10
	v_mul_f32_e32 v11, v61, v11
	v_cvt_pk_bf16_f32 v8, v8, v9
	v_cvt_pk_bf16_f32 v9, v10, v11
	ds_write_b64 v21, v[8:9]
	v_mul_f32_e32 v12, v111, v20
	v_mul_f32_e32 v13, v116, v20
	v_mul_f32_e32 v28, v117, v20
	v_mul_f32_e32 v29, v118, v20
	v_lshlrev_b32_e32 v184, 5, v102
	v_pk_mul_f32 v[14:15], v[14:15], v[20:21] op_sel_hi:[1,0]
	v_pk_mul_f32 v[40:41], v[40:41], v[20:21] op_sel_hi:[1,0]
	v_pk_mul_f32 v[6:7], v[6:7], v[20:21] op_sel_hi:[1,0]
	v_pk_mul_f32 v[4:5], v[4:5], v[20:21] op_sel_hi:[1,0]
	v_pk_mul_f32 v[0:1], v[0:1], v[20:21] op_sel_hi:[1,0]
	v_pk_mul_f32 v[2:3], v[2:3], v[20:21] op_sel_hi:[1,0]
	v_pk_mul_f32 v[38:39], v[38:39], v[20:21] op_sel_hi:[1,0]
	v_pk_mul_f32 v[24:25], v[24:25], v[20:21] op_sel_hi:[1,0]
	v_pk_mul_f32 v[22:23], v[22:23], v[20:21] op_sel_hi:[1,0]
	v_pk_mul_f32 v[26:27], v[26:27], v[20:21] op_sel_hi:[1,0]
	v_pk_mul_f32 v[16:17], v[16:17], v[20:21] op_sel_hi:[1,0]
	v_pk_mul_f32 v[18:19], v[18:19], v[20:21] op_sel_hi:[1,0]
	s_waitcnt vmcnt(0) lgkmcnt(0)
	v_mul_f32_e32 v8, v194, v12
	v_mul_f32_e32 v12, v112, v20
	v_mul_f32_e32 v9, v12, v195
	v_mul_f32_e32 v12, v113, v20
	v_mul_f32_e32 v10, v12, v196
	v_mul_f32_e32 v12, v114, v20
	v_mul_f32_e32 v11, v12, v197
	v_cvt_pk_bf16_f32 v8, v8, v9
	v_cvt_pk_bf16_f32 v9, v10, v11
	ds_write_b64 v21, v[8:9] offset:16
	v_mul_f32_e32 v12, v115, v20
	s_waitcnt vmcnt(0) lgkmcnt(0)
	v_mul_f32_e32 v8, v12, v198
	v_mul_f32_e32 v9, v13, v199
	v_mul_f32_e32 v10, v28, v200
	v_mul_f32_e32 v11, v29, v201
	v_cvt_pk_bf16_f32 v8, v8, v9
	v_cvt_pk_bf16_f32 v9, v10, v11
	ds_write_b64 v21, v[8:9] offset:32
	v_mul_f32_e32 v12, v119, v20
	v_mul_f32_e32 v13, v120, v20
	v_mul_f32_e32 v28, v121, v20
	v_mul_f32_e32 v29, v122, v20
	s_waitcnt vmcnt(0) lgkmcnt(0)
	v_mul_f32_e32 v8, v12, v202
	v_mul_f32_e32 v9, v13, v203
	v_mul_f32_e32 v10, v28, v204
	v_mul_f32_e32 v11, v29, v205
	v_cvt_pk_bf16_f32 v8, v8, v9
	v_cvt_pk_bf16_f32 v9, v10, v11
	ds_write_b64 v21, v[8:9] offset:48
	v_mul_f32_e32 v12, v123, v20
	v_mul_f32_e32 v13, v124, v20
	v_mul_f32_e32 v28, v125, v20
	v_mul_f32_e32 v29, v126, v20
	s_waitcnt vmcnt(0) lgkmcnt(0)
	v_mul_f32_e32 v8, v12, v206
	v_mul_f32_e32 v9, v13, v207
	v_mul_f32_e32 v10, v28, v208
	v_mul_f32_e32 v11, v29, v209
	v_cvt_pk_bf16_f32 v8, v8, v9
	v_cvt_pk_bf16_f32 v9, v10, v11
	ds_write_b64 v21, v[8:9] offset:64
	v_mul_f32_e32 v12, v127, v20
	v_mul_f32_e32 v13, v128, v20
	v_mul_f32_e32 v28, v129, v20
	v_mul_f32_e32 v29, v130, v20
	s_waitcnt vmcnt(0) lgkmcnt(0)
	v_mul_f32_e32 v8, v12, v210
	v_mul_f32_e32 v9, v13, v211
	v_mul_f32_e32 v10, v28, v212
	v_mul_f32_e32 v11, v29, v213
	v_cvt_pk_bf16_f32 v8, v8, v9
	v_cvt_pk_bf16_f32 v9, v10, v11
	ds_write_b64 v21, v[8:9] offset:80
	v_mul_f32_e32 v12, v80, v20
	v_mul_f32_e32 v13, v81, v20
	v_mul_f32_e32 v28, v82, v20
	v_mul_f32_e32 v29, v83, v20
	s_waitcnt vmcnt(0) lgkmcnt(0)
	v_mul_f32_e32 v8, v12, v214
	v_mul_f32_e32 v9, v13, v215
	v_mul_f32_e32 v10, v28, v216
	v_mul_f32_e32 v11, v29, v217
	v_cvt_pk_bf16_f32 v8, v8, v9
	v_cvt_pk_bf16_f32 v9, v10, v11
	ds_write_b64 v21, v[8:9] offset:96
	v_mul_f32_e32 v12, v72, v20
	v_mul_f32_e32 v13, v73, v20
	v_mul_f32_e32 v28, v74, v20
	v_mul_f32_e32 v29, v75, v20
	s_waitcnt vmcnt(0) lgkmcnt(0)
	v_mul_f32_e32 v8, v12, v218
	v_mul_f32_e32 v9, v13, v219
	v_mul_f32_e32 v10, v28, v220
	v_mul_f32_e32 v11, v29, v221
	v_cvt_pk_bf16_f32 v8, v8, v9
	v_cvt_pk_bf16_f32 v9, v10, v11
	ds_write_b64 v21, v[8:9] offset:112
	v_mul_f32_e32 v12, v68, v20
	v_mul_f32_e32 v13, v69, v20
	v_mul_f32_e32 v28, v70, v20
	v_mul_f32_e32 v29, v71, v20
	s_waitcnt vmcnt(0) lgkmcnt(0)
	v_mul_f32_e32 v8, v12, v222
	v_mul_f32_e32 v9, v13, v223
	v_mul_f32_e32 v10, v28, v224
	v_mul_f32_e32 v11, v29, v225
	v_cvt_pk_bf16_f32 v8, v8, v9
	v_cvt_pk_bf16_f32 v9, v10, v11
	ds_write_b64 v21, v[8:9] offset:128
	v_mul_f32_e32 v12, v64, v20
	v_mul_f32_e32 v13, v65, v20
	v_mul_f32_e32 v28, v66, v20
	v_mul_f32_e32 v29, v67, v20
	s_waitcnt vmcnt(0) lgkmcnt(0)
	v_mul_f32_e32 v8, v12, v232
	v_mul_f32_e32 v9, v13, v233
	v_mul_f32_e32 v10, v28, v234
	v_mul_f32_e32 v11, v29, v235
	v_cvt_pk_bf16_f32 v8, v8, v9
	v_cvt_pk_bf16_f32 v9, v10, v11
	ds_write_b64 v21, v[8:9] offset:144
	v_mul_f32_e32 v12, v54, v20
	v_mul_f32_e32 v13, v55, v20
	v_mul_f32_e32 v28, v56, v20
	v_mul_f32_e32 v29, v57, v20
	s_waitcnt vmcnt(0) lgkmcnt(0)
	v_mul_f32_e32 v8, v12, v236
	v_mul_f32_e32 v9, v13, v237
	v_mul_f32_e32 v10, v28, v238
	v_mul_f32_e32 v11, v29, v239
	v_cvt_pk_bf16_f32 v8, v8, v9
	v_cvt_pk_bf16_f32 v9, v10, v11
	ds_write_b64 v21, v[8:9] offset:160
	v_mul_f32_e32 v12, v50, v20
	v_mul_f32_e32 v13, v51, v20
	v_mul_f32_e32 v28, v52, v20
	v_mul_f32_e32 v29, v53, v20
	s_waitcnt vmcnt(0) lgkmcnt(0)
	v_mul_f32_e32 v8, v12, v240
	v_mul_f32_e32 v9, v13, v241
	v_mul_f32_e32 v10, v28, v242
	v_mul_f32_e32 v11, v29, v243
	v_cvt_pk_bf16_f32 v8, v8, v9
	v_cvt_pk_bf16_f32 v9, v10, v11
	ds_write_b64 v21, v[8:9] offset:176
	v_mul_f32_e32 v12, v48, v20
	v_mul_f32_e32 v13, v33, v20
	v_mul_f32_e32 v28, v49, v20
	v_mul_f32_e32 v29, v35, v20
	s_waitcnt vmcnt(0) lgkmcnt(0)
	v_mul_f32_e32 v8, v12, v244
	v_mul_f32_e32 v9, v13, v245
	v_mul_f32_e32 v10, v28, v246
	v_mul_f32_e32 v11, v29, v247
	v_cvt_pk_bf16_f32 v8, v8, v9
	v_cvt_pk_bf16_f32 v9, v10, v11
	ds_write_b64 v21, v[8:9] offset:192
	v_mul_f32_e32 v12, v131, v20
	v_mul_f32_e32 v13, v132, v20
	v_mul_f32_e32 v28, v133, v20
	v_mul_f32_e32 v29, v134, v20
	s_waitcnt vmcnt(0) lgkmcnt(0)
; DEV void epi_uq(f32x16 (&acc)[1][6], const Params& P, int layer, int batch, int m0, int head, int wid, int r32, int hi, char* lds) {
;     ...
; #pragma unroll
;   for (int ni = 0; ni < 4; ++ni)
; #pragma unroll
;     for (int r4 = 0; r4 < 4; ++r4) {
;       const int c = ni * 32 + r4 * 8 + hi * 4;
;       const float4 gg = *reinterpret_cast<const float4*>(g + c);
;       const f32x16& a = acc[0][ni];
;       st4lds(dst, c, a[r4 * 4] * inv * gg.x, a[r4 * 4 + 1] * inv * gg.y, a[r4 * 4 + 2] * inv * gg.z, a[r4 * 4 + 3] * inv * gg.w);
;     }
;   const int pos = batch ? t : (t & 4095);
;   const float2* rp = WS{P.ws}.rope() + (long)pos * 32;
; #pragma unroll
;   for (int r4 = 0; r4 < 4; ++r4) {
;     const int i = r4 * 8 + hi * 4;
;     const float4 g1 = *reinterpret_cast<const float4*>(g + 128 + i), g2 = *reinterpret_cast<const float4*>(g + 160 + i);
;     const float4 cs01 = *reinterpret_cast<const float4*>(rp + i), cs23 = *reinterpret_cast<const float4*>(rp + i + 2);
;     const float x1[4] = {acc[0][4][r4 * 4] * inv * g1.x, acc[0][4][r4 * 4 + 1] * inv * g1.y, acc[0][4][r4 * 4 + 2] * inv * g1.z, acc[0][4][r4 * 4 + 3] * inv * g1.w};
;     const float x2[4] = {acc[0][5][r4 * 4] * inv * g2.x, acc[0][5][r4 * 4 + 1] * inv * g2.y, acc[0][5][r4 * 4 + 2] * inv * g2.z, acc[0][5][r4 * 4 + 3] * inv * g2.w};
;     const float cc[4] = {cs01.x, cs01.z, cs23.x, cs23.z}, sn[4] = {cs01.y, cs01.w, cs23.y, cs23.w};
;     st4lds(dst, 128 + i, x1[0] * cc[0] - x2[0] * sn[0], x1[1] * cc[1] - x2[1] * sn[1], x1[2] * cc[2] - x2[2] * sn[2], x1[3] * cc[3] - x2[3] * sn[3]);
;     st4lds(dst, 160 + i, x1[0] * sn[0] + x2[0] * cc[0], x1[1] * sn[1] + x2[1] * cc[1], x1[2] * sn[2] + x2[2] * cc[2], x1[3] * sn[3] + x2[3] * cc[3]);
;   }
	v_mul_f32_e32 v8, v12, v248
	v_mul_f32_e32 v9, v13, v249
	v_mul_f32_e32 v10, v28, v250
	v_mul_f32_e32 v11, v29, v251
	v_cvt_pk_bf16_f32 v8, v8, v9
	v_cvt_pk_bf16_f32 v9, v10, v11
	ds_write_b64 v21, v[8:9] offset:208
	v_mul_f32_e32 v12, v135, v20
	v_mul_f32_e32 v13, v136, v20
	v_mul_f32_e32 v28, v137, v20
	v_mul_f32_e32 v29, v138, v20
	s_waitcnt vmcnt(0) lgkmcnt(0)
	v_mul_f32_e32 v8, v12, v170
	v_mul_f32_e32 v9, v13, v171
	v_mul_f32_e32 v10, v28, v172
	v_mul_f32_e32 v11, v29, v173
	v_cvt_pk_bf16_f32 v8, v8, v9
	v_cvt_pk_bf16_f32 v9, v10, v11
	ds_write_b64 v21, v[8:9] offset:224
	v_mul_f32_e32 v12, v139, v20
	v_mul_f32_e32 v13, v140, v20
	v_mul_f32_e32 v28, v141, v20
	v_mul_f32_e32 v29, v47, v20
	s_waitcnt vmcnt(0) lgkmcnt(0)
	v_mul_f32_e32 v8, v12, v174
	v_bitop3_b32 v12, v99, s3, v101 bitop3:0xc8
	v_cndmask_b32_e64 v12, v96, v12, s[26:27]
	v_mul_f32_e32 v9, v13, v175
	v_ashrrev_i32_e32 v13, 31, v12
	v_mul_f32_e32 v10, v28, v176
	v_mul_f32_e32 v11, v29, v177
	v_cvt_pk_bf16_f32 v8, v8, v9
	v_cvt_pk_bf16_f32 v9, v10, v11
	ds_write_b64 v21, v[8:9] offset:240
	v_lshlrev_b64 v[12:13], 8, v[12:13]
	flat_load_dwordx4 v[8:11], v[36:37] offset:1792
	flat_load_dwordx4 v[48:51], v[36:37] offset:1920
	v_lshl_add_u64 v[12:13], s[12:13], 0, v[12:13]
	v_lshl_add_u64 v[28:29], v[12:13], 0, v[184:185]
	flat_load_dwordx4 v[52:55], v[28:29]
	flat_load_dwordx4 v[56:59], v[28:29] offset:16
	v_pk_mul_f32 v[12:13], v[42:43], v[20:21] op_sel_hi:[1,0]
	v_pk_mul_f32 v[42:43], v[44:45], v[20:21] op_sel_hi:[1,0]
	s_waitcnt vmcnt(0) lgkmcnt(0)
	v_mov_b32_e32 v44, v8
	v_mov_b32_e32 v45, v48
	v_mov_b32_e32 v48, v9
	v_mov_b32_e32 v8, v10
	v_mov_b32_e32 v9, v50
	v_mov_b32_e32 v50, v11
	v_pk_mul_f32 v[10:11], v[12:13], v[44:45]
	v_pk_mul_f32 v[12:13], v[42:43], v[48:49]
	v_pk_mul_f32 v[8:9], v[14:15], v[8:9]
	v_pk_mul_f32 v[14:15], v[40:41], v[50:51]
	v_pk_mul_f32 v[40:41], v[10:11], v[52:53]
	v_pk_mul_f32 v[42:43], v[12:13], v[54:55]
	v_pk_mul_f32 v[44:45], v[8:9], v[56:57]
	v_pk_mul_f32 v[48:49], v[14:15], v[58:59]
	v_pk_mul_f32 v[10:11], v[10:11], v[52:53] op_sel:[1,0] op_sel_hi:[0,1]
	v_pk_mul_f32 v[12:13], v[12:13], v[54:55] op_sel:[1,0] op_sel_hi:[0,1]
	v_pk_mul_f32 v[8:9], v[8:9], v[56:57] op_sel:[1,0] op_sel_hi:[0,1]
	v_pk_mul_f32 v[14:15], v[14:15], v[58:59] op_sel:[1,0] op_sel_hi:[0,1]
	v_sub_f32_e32 v33, v40, v41
	v_sub_f32_e32 v35, v42, v43
	v_sub_f32_e32 v40, v44, v45
	v_sub_f32_e32 v41, v48, v49
	v_add_f32_e32 v10, v10, v11
	v_add_f32_e32 v11, v12, v13
	v_add_f32_e32 v12, v8, v9
	v_cvt_pk_bf16_f32 v8, v33, v35
	v_cvt_pk_bf16_f32 v9, v40, v41
	v_add_f32_e32 v13, v14, v15
	ds_write_b64 v21, v[8:9] offset:256
	v_cvt_pk_bf16_f32 v8, v10, v11
	v_cvt_pk_bf16_f32 v9, v12, v13
	ds_write_b64 v21, v[8:9] offset:320
	flat_load_dwordx4 v[8:11], v[36:37] offset:1824
	flat_load_dwordx4 v[12:15], v[36:37] offset:1952
	flat_load_dwordx4 v[40:43], v[28:29] offset:64
	flat_load_dwordx4 v[48:51], v[28:29] offset:80
	v_and_b32_e32 v33, 63, v100
	v_mul_lo_u16_e32 v35, 43, v33
	v_or_b32_e32 v47, 0xc0, v33
	v_or_b32_e32 v52, 0x1c0, v33
	v_or_b32_e32 v53, 0x280, v33
	v_or_b32_e32 v54, 0x240, v33
	v_or_b32_e32 v55, 0x2c0, v33
	v_lshrrev_b16_e32 v35, 10, v35
	v_mul_lo_u16_e32 v56, 0xab, v47
	v_mul_u32_u24_e32 v60, 0xaab, v52
	v_mul_u32_u24_e32 v62, 0xaab, v54
	v_mul_u32_u24_e32 v63, 0xaab, v53
	v_mul_u32_u24_e32 v64, 0xaab, v55
	v_lshrrev_b16_e32 v56, 12, v56
	v_mul_u32_u24_e32 v65, 0x190, v35
	v_lshrrev_b32_e32 v71, 16, v63
	s_waitcnt vmcnt(0) lgkmcnt(0)
	v_mov_b32_e32 v44, v8
	v_mov_b32_e32 v45, v12
	v_mov_b32_e32 v12, v9
	v_mov_b32_e32 v8, v10
	v_mov_b32_e32 v9, v14
	v_mov_b32_e32 v14, v11
	v_pk_mul_f32 v[6:7], v[6:7], v[44:45]
	v_pk_mul_f32 v[4:5], v[4:5], v[12:13]
	v_pk_mul_f32 v[0:1], v[0:1], v[8:9]
	v_pk_mul_f32 v[2:3], v[2:3], v[14:15]
	v_pk_mul_f32 v[8:9], v[6:7], v[40:41]
	v_pk_mul_f32 v[10:11], v[4:5], v[42:43]
	v_pk_mul_f32 v[12:13], v[0:1], v[48:49]
	v_pk_mul_f32 v[14:15], v[2:3], v[50:51]
	v_pk_mul_f32 v[4:5], v[4:5], v[42:43] op_sel:[1,0] op_sel_hi:[0,1]
	v_pk_mul_f32 v[0:1], v[0:1], v[48:49] op_sel:[1,0] op_sel_hi:[0,1]
	v_pk_mul_f32 v[6:7], v[6:7], v[40:41] op_sel:[1,0] op_sel_hi:[0,1]
	v_pk_mul_f32 v[2:3], v[2:3], v[50:51] op_sel:[1,0] op_sel_hi:[0,1]
	v_sub_f32_e32 v8, v8, v9
	v_sub_f32_e32 v9, v10, v11
	v_sub_f32_e32 v10, v12, v13
	v_sub_f32_e32 v11, v14, v15
	v_add_f32_e32 v4, v4, v5
	v_add_f32_e32 v5, v0, v1
	v_cvt_pk_bf16_f32 v0, v8, v9
	v_cvt_pk_bf16_f32 v1, v10, v11
	v_add_f32_e32 v6, v6, v7
	v_add_f32_e32 v2, v2, v3
	ds_write_b64 v21, v[0:1] offset:272
	v_cvt_pk_bf16_f32 v0, v6, v4
	v_cvt_pk_bf16_f32 v1, v5, v2
	ds_write_b64 v21, v[0:1] offset:336
	flat_load_dwordx4 v[12:15], v[36:37] offset:1856
	flat_load_dwordx4 v[8:11], v[36:37] offset:1984
	flat_load_dwordx4 v[0:3], v[28:29] offset:128
	flat_load_dwordx4 v[4:7], v[28:29] offset:144
	v_or_b32_e32 v44, 64, v33
	v_or_b32_e32 v45, 0x80, v33
	v_mul_lo_u16_e32 v42, 43, v44
	v_mul_lo_u16_e32 v43, 0xab, v45
	v_lshrrev_b16_e32 v66, 10, v42
	v_lshrrev_b16_e32 v67, 12, v43
	v_or_b32_e32 v48, 0x100, v33
	v_or_b32_e32 v49, 0x180, v33
	v_or_b32_e32 v50, 0x140, v33
	v_or_b32_e32 v51, 0x200, v33
	v_mul_u32_u24_e32 v57, 0xaab, v48
	v_mul_u32_u24_e32 v58, 0xaab, v50
	v_mul_u32_u24_e32 v59, 0xaab, v49
	v_mul_u32_u24_e32 v61, 0xaab, v51
	v_mad_i32_i24 v33, v35, s58, v33
	v_lshrrev_b32_e32 v57, 16, v57
	v_lshrrev_b32_e32 v68, 16, v58
	v_lshrrev_b32_e32 v69, 16, v59
	v_perm_b32 v58, v59, v58, s44
	v_lshrrev_b32_e32 v59, 16, v60
	v_lshrrev_b32_e32 v70, 16, v61
	v_perm_b32 v60, v61, v60, s44
	v_lshrrev_b32_e32 v61, 16, v62
	v_perm_b32 v62, v63, v62, s44
	v_lshrrev_b32_e32 v63, 16, v64
	v_lshlrev_b32_e32 v64, 4, v33
	v_mul_u32_u24_e32 v35, 0x300, v35
	v_lshlrev_b32_e32 v184, 1, v35
	v_mov_b32_e32 v35, v30
	v_mov_b64_e32 v[40:41], s[14:15]
	v_mad_i64_i32 v[40:41], s[2:3], v99, s39, v[40:41]
	v_lshl_add_u64 v[40:41], v[40:41], 0, s[22:23]
	v_mad_i32_i24 v55, v63, s58, v55
	v_lshlrev_b32_e32 v80, 4, v55
	s_waitcnt vmcnt(0) lgkmcnt(0)
; #define LDSP(T) __attribute__((address_space(3))) T*
; template <int NCH, int STRIDE> DEV void slab_flush(char* slab, u16* grow0, int gstride, int lane) {
;   asm volatile("s_waitcnt lgkmcnt(0)" ::: "memory");
; #pragma unroll
;   for (int i = 0; i < NCH / 2; ++i) {
;     const int q = i * 64 + lane, row = q / NCH, cc = q - row * NCH;
;     const u32x4 v = *(LDSP(const u32x4))(slab + row * STRIDE + cc * 16);
;     *reinterpret_cast<u32x4*>(grow0 + (long)row * gstride + cc * 8) = v;
;   }
;   asm volatile("s_waitcnt lgkmcnt(0)" ::: "memory");
; }
; DEV void epi_uq(f32x16 (&acc)[1][6], const Params& P, int layer, int batch, int m0, int head, int wid, int r32, int hi, char* lds) {
;     ...
;   for (int r4 = 0; r4 < 4; ++r4) {
;     const int i = r4 * 8 + hi * 4;
;     const float4 g1 = *reinterpret_cast<const float4*>(g + 128 + i), g2 = *reinterpret_cast<const float4*>(g + 160 + i);
;     const float4 cs01 = *reinterpret_cast<const float4*>(rp + i), cs23 = *reinterpret_cast<const float4*>(rp + i + 2);
;     const float x1[4] = {acc[0][4][r4 * 4] * inv * g1.x, acc[0][4][r4 * 4 + 1] * inv * g1.y, acc[0][4][r4 * 4 + 2] * inv * g1.z, acc[0][4][r4 * 4 + 3] * inv * g1.w};
;     const float x2[4] = {acc[0][5][r4 * 4] * inv * g2.x, acc[0][5][r4 * 4 + 1] * inv * g2.y, acc[0][5][r4 * 4 + 2] * inv * g2.z, acc[0][5][r4 * 4 + 3] * inv * g2.w};
;     const float cc[4] = {cs01.x, cs01.z, cs23.x, cs23.z}, sn[4] = {cs01.y, cs01.w, cs23.y, cs23.w};
;     st4lds(dst, 128 + i, x1[0] * cc[0] - x2[0] * sn[0], x1[1] * cc[1] - x2[1] * sn[1], x1[2] * cc[2] - x2[2] * sn[2], x1[3] * cc[3] - x2[3] * sn[3]);
;     st4lds(dst, 160 + i, x1[0] * sn[0] + x2[0] * cc[0], x1[1] * sn[1] + x2[1] * cc[1], x1[2] * sn[2] + x2[2] * cc[2], x1[3] * sn[3] + x2[3] * cc[3]);
;   }
;   slab_flush<24, 400>(slab, WS{P.ws}.QB() + (long)(m0 + wid * 32) * 768 + head * 192, 768, hi * 32 + r32);
	v_mov_b32_e32 v42, v12
	v_mov_b32_e32 v43, v8
	v_mov_b32_e32 v8, v13
	v_mov_b32_e32 v12, v14
	v_mov_b32_e32 v13, v10
	v_mov_b32_e32 v10, v15
	v_pk_mul_f32 v[14:15], v[38:39], v[42:43]
	v_pk_mul_f32 v[8:9], v[24:25], v[8:9]
	v_pk_mul_f32 v[12:13], v[22:23], v[12:13]
	v_pk_mul_f32 v[10:11], v[26:27], v[10:11]
	v_pk_mul_f32 v[22:23], v[14:15], v[0:1]
	v_pk_mul_f32 v[24:25], v[8:9], v[2:3]
	v_pk_mul_f32 v[26:27], v[12:13], v[4:5]
	v_pk_mul_f32 v[38:39], v[10:11], v[6:7]
	v_pk_mul_f32 v[0:1], v[14:15], v[0:1] op_sel:[1,0] op_sel_hi:[0,1]
	v_pk_mul_f32 v[2:3], v[8:9], v[2:3] op_sel:[1,0] op_sel_hi:[0,1]
	v_pk_mul_f32 v[4:5], v[12:13], v[4:5] op_sel:[1,0] op_sel_hi:[0,1]
	v_pk_mul_f32 v[6:7], v[10:11], v[6:7] op_sel:[1,0] op_sel_hi:[0,1]
	v_sub_f32_e32 v8, v22, v23
	v_sub_f32_e32 v9, v24, v25
	v_sub_f32_e32 v10, v26, v27
	v_sub_f32_e32 v11, v38, v39
	v_add_f32_e32 v12, v0, v1
	v_cvt_pk_bf16_f32 v0, v8, v9
	v_cvt_pk_bf16_f32 v1, v10, v11
	v_add_f32_e32 v2, v2, v3
	v_add_f32_e32 v3, v4, v5
	v_add_f32_e32 v4, v6, v7
	ds_write_b64 v21, v[0:1] offset:288
	v_cvt_pk_bf16_f32 v0, v12, v2
	v_cvt_pk_bf16_f32 v1, v3, v4
	ds_write_b64 v21, v[0:1] offset:352
	flat_load_dwordx4 v[0:3], v[36:37] offset:1888
	flat_load_dwordx4 v[4:7], v[36:37] offset:2016
	flat_load_dwordx4 v[8:11], v[28:29] offset:192
	flat_load_dwordx4 v[12:15], v[28:29] offset:208
	v_lshlrev_b32_e32 v22, 3, v33
	v_mad_i32_i24 v24, v66, s58, v44
	v_mad_i32_i24 v33, v56, s58, v47
	v_mad_i32_i24 v29, v57, s58, v48
	v_mul_u32_u24_e32 v25, 0x190, v66
	v_mad_i32_i24 v26, v67, s58, v45
	v_mul_u32_u24_e32 v27, 0x190, v67
	v_mul_u32_u24_e32 v45, 0x300, v67
	v_mul_u32_u24_e32 v39, 0x190, v57
	v_pk_mul_lo_u16 v42, v58, s37 op_sel_hi:[1,0]
	v_mad_i32_i24 v43, v69, s58, v49
	v_mad_i32_i24 v44, v59, s58, v52
	v_mad_i32_i24 v52, v71, s58, v53
	v_add3_u32 v53, v46, v65, v64
	v_lshlrev_b32_e32 v64, 4, v24
	v_lshlrev_b32_e32 v67, 4, v33
	v_lshlrev_b32_e32 v28, 3, v33
	v_lshlrev_b32_e32 v33, 4, v29
	v_mul_u32_u24_e32 v37, 0x190, v56
	v_mul_u32_u24_e32 v47, 0x300, v56
	v_mul_u32_u24_e32 v56, 0x300, v57
	v_mad_i32_i24 v38, v68, s58, v50
	v_mul_u32_u24_e32 v57, 0x300, v68
	v_pk_mul_lo_u16 v48, v60, s37 op_sel_hi:[1,0]
	v_mad_i32_i24 v49, v70, s58, v51
	v_mul_u32_u24_e32 v60, 0x300, v70
	v_mad_i32_i24 v50, v61, s58, v54
	v_mul_u32_u24_e32 v54, 0x300, v61
	v_mul_u32_u24_e32 v61, 0x300, v71
	v_and_b32_e32 v68, 0xfff0, v42
	v_lshrrev_b32_e32 v70, 16, v42
	v_lshlrev_b32_e32 v71, 4, v43
	v_lshlrev_b32_e32 v42, 3, v43
	v_add3_u32 v43, v46, v25, v64
	v_add3_u32 v64, v46, v39, v33
	v_mov_b32_e32 v33, v31
	v_pk_mul_f32 v[30:31], v[34:35], v[20:21] op_sel_hi:[1,0]
	v_pk_mul_f32 v[32:33], v[32:33], v[20:21] op_sel_hi:[1,0]
	v_ashrrev_i32_e32 v23, 31, v22
	v_mul_u32_u24_e32 v66, 0x300, v66
	v_lshlrev_b32_e32 v24, 3, v24
	v_ashrrev_i32_e32 v25, 31, v24
	v_lshlrev_b32_e32 v65, 4, v26
	v_and_b32_e32 v72, 0xfff0, v48
	v_lshrrev_b32_e32 v74, 16, v48
	v_lshlrev_b32_e32 v75, 4, v49
	v_lshlrev_b32_e32 v48, 3, v49
	v_add3_u32 v49, v46, v27, v65
	v_lshlrev_b32_e32 v26, 3, v26
	v_ashrrev_i32_e32 v27, 31, v26
	v_pk_mul_lo_u16 v51, v62, s37 op_sel_hi:[1,0]
	v_lshlrev_b32_e32 v36, 3, v29
	v_and_b32_e32 v76, 0xfff0, v51
	v_lshrrev_b32_e32 v78, 16, v51
	v_add3_u32 v51, v46, v37, v67
	v_ashrrev_i32_e32 v29, 31, v28
	v_ashrrev_i32_e32 v37, 31, v36
	v_mul_u32_u24_e32 v58, 0x300, v69
	v_lshlrev_b32_e32 v69, 4, v38
	v_add3_u32 v65, v46, v68, v69
	v_lshlrev_b32_e32 v38, 3, v38
	v_ashrrev_i32_e32 v39, 31, v38
	v_lshlrev_b32_e32 v73, 4, v44
	v_mul_u32_u24_e32 v59, 0x300, v59
	v_lshlrev_b32_e32 v44, 3, v44
	v_lshlrev_b32_e32 v77, 4, v50
	v_lshlrev_b32_e32 v50, 3, v50
	v_lshlrev_b32_e32 v79, 4, v52
	v_lshlrev_b32_e32 v52, 3, v52
	v_mul_u32_u24_e32 v62, 0x190, v63
	v_mul_u32_u24_e32 v63, 0x300, v63
	s_waitcnt vmcnt(0) lgkmcnt(0)
	v_mov_b32_e32 v34, v0
	v_mov_b32_e32 v35, v4
	v_mov_b32_e32 v4, v1
	v_mov_b32_e32 v0, v2
	v_mov_b32_e32 v1, v6
	v_mov_b32_e32 v6, v3
	v_pk_mul_f32 v[2:3], v[16:17], v[34:35]
	v_pk_mul_f32 v[4:5], v[18:19], v[4:5]
	v_pk_mul_f32 v[0:1], v[30:31], v[0:1]
	v_pk_mul_f32 v[6:7], v[32:33], v[6:7]
	v_pk_mul_f32 v[16:17], v[2:3], v[8:9]
	v_pk_mul_f32 v[18:19], v[4:5], v[10:11]
	v_pk_mul_f32 v[30:31], v[0:1], v[12:13]
	v_pk_mul_f32 v[32:33], v[6:7], v[14:15]
	v_pk_mul_f32 v[2:3], v[2:3], v[8:9] op_sel:[1,0] op_sel_hi:[0,1]
	v_pk_mul_f32 v[4:5], v[4:5], v[10:11] op_sel:[1,0] op_sel_hi:[0,1]
	v_pk_mul_f32 v[0:1], v[0:1], v[12:13] op_sel:[1,0] op_sel_hi:[0,1]
	v_pk_mul_f32 v[6:7], v[6:7], v[14:15] op_sel:[1,0] op_sel_hi:[0,1]
	v_sub_f32_e32 v8, v16, v17
	v_sub_f32_e32 v9, v18, v19
	v_sub_f32_e32 v10, v30, v31
	v_sub_f32_e32 v11, v32, v33
	v_add_f32_e32 v2, v2, v3
	v_add_f32_e32 v3, v4, v5
	v_add_f32_e32 v4, v0, v1
	v_cvt_pk_bf16_f32 v0, v8, v9
	v_cvt_pk_bf16_f32 v1, v10, v11
	v_add_f32_e32 v5, v6, v7
	ds_write_b64 v21, v[0:1] offset:304
	v_cvt_pk_bf16_f32 v0, v2, v3
	v_cvt_pk_bf16_f32 v1, v4, v5
	ds_write_b64 v21, v[0:1] offset:368
	s_waitcnt lgkmcnt(0)
	ds_read_b128 v[0:3], v53
	v_lshl_add_u64 v[4:5], v[40:41], 0, v[184:185]
	v_lshl_add_u64 v[4:5], v[22:23], 1, v[4:5]
	v_lshlrev_b32_e32 v184, 1, v66
	v_add3_u32 v6, v46, v70, v71
	s_waitcnt lgkmcnt(0)
	flat_store_dwordx4 v[4:5], v[0:3]
	ds_read_b128 v[0:3], v43
	v_lshl_add_u64 v[4:5], v[40:41], 0, v[184:185]
	v_lshl_add_u64 v[4:5], v[24:25], 1, v[4:5]
	v_lshlrev_b32_e32 v184, 1, v45
	v_ashrrev_i32_e32 v43, 31, v42
	s_waitcnt lgkmcnt(0)
	flat_store_dwordx4 v[4:5], v[0:3]
	ds_read_b128 v[0:3], v49
	v_lshl_add_u64 v[4:5], v[40:41], 0, v[184:185]
	v_lshl_add_u64 v[4:5], v[26:27], 1, v[4:5]
	v_lshlrev_b32_e32 v184, 1, v47
	v_add3_u32 v7, v46, v72, v73
	s_waitcnt lgkmcnt(0)
; DEV int opaque_tid() { int t = threadIdx.x; asm volatile("" : "+v"(t)); return t; }
; #define LDSP(T) __attribute__((address_space(3))) T*
; #define GLOAD(kt, buf) do { _Pragma("unroll") for (int i = 0; i < 4; ++i) glds16(Ap + (long)i * 64 * lda + (kt) * 64, As + (buf) * 32768 + soff + i * 8192); \
;     _Pragma("unroll") for (int i = 0; i < NB; ++i) glds16(Bp + (long)i * 64 * ldb + (kt) * 64, Bs + (buf) * 32768 + soff + i * 8192); } while (0)
; template <int NCH, int STRIDE> DEV void slab_flush(char* slab, u16* grow0, int gstride, int lane) {
;   asm volatile("s_waitcnt lgkmcnt(0)" ::: "memory");
; #pragma unroll
;   for (int i = 0; i < NCH / 2; ++i) {
;     const int q = i * 64 + lane, row = q / NCH, cc = q - row * NCH;
;     const u32x4 v = *(LDSP(const u32x4))(slab + row * STRIDE + cc * 16);
;     *reinterpret_cast<u32x4*>(grow0 + (long)row * gstride + cc * 8) = v;
;   }
;   asm volatile("s_waitcnt lgkmcnt(0)" ::: "memory");
; }
; template <int WM, int WN, int BN, int EPI>
; DEV void gemm_tile(const u16* __restrict__ A, int lda, const u16* __restrict__ Bt, int ldb, int K, int m0, char* lds,
;                    const Params& P, int layer, int batch, int nt) {
;     ...
;   const int tid = opaque_tid(), wid = tid >> 6, lane = tid & 63, r32 = lane & 31, hi = lane >> 5;
;   const int wm = wid / WN, wn = wid % WN;
;   char* As = lds; char* Bs = lds + 65536;
;   f32x16 acc[MI][NI];
; #pragma unroll
;   for (int mi = 0; mi < MI; ++mi)
; #pragma unroll
;     for (int ni = 0; ni < NI; ++ni) acc[mi][ni] = f32x16{};
;   const int srow = tid >> 3, sch = (tid & 7) ^ ((srow >> 1) & 7);
;   const u16* Ap = A + (long)(m0 + srow) * lda + sch * 8;
;   const u16* Bp = Bt + (long)srow * ldb + sch * 8;
;   const int soff = tid * 16;
;     ...
;   GLOAD(0, 0); asm volatile("s_waitcnt vmcnt(0)" ::: "memory"); __syncthreads();
	flat_store_dwordx4 v[4:5], v[0:3]
	ds_read_b128 v[0:3], v51
	v_lshl_add_u64 v[4:5], v[40:41], 0, v[184:185]
	v_lshl_add_u64 v[4:5], v[28:29], 1, v[4:5]
	v_lshlrev_b32_e32 v184, 1, v56
	v_ashrrev_i32_e32 v45, 31, v44
	s_waitcnt lgkmcnt(0)
	flat_store_dwordx4 v[4:5], v[0:3]
	ds_read_b128 v[0:3], v64
	v_lshl_add_u64 v[4:5], v[40:41], 0, v[184:185]
	v_lshl_add_u64 v[4:5], v[36:37], 1, v[4:5]
	v_lshlrev_b32_e32 v184, 1, v57
	v_add3_u32 v8, v46, v74, v75
	s_waitcnt lgkmcnt(0)
	flat_store_dwordx4 v[4:5], v[0:3]
	ds_read_b128 v[0:3], v65
	v_lshl_add_u64 v[4:5], v[40:41], 0, v[184:185]
	v_lshl_add_u64 v[4:5], v[38:39], 1, v[4:5]
	v_lshlrev_b32_e32 v184, 1, v58
	v_ashrrev_i32_e32 v49, 31, v48
	s_waitcnt lgkmcnt(0)
	flat_store_dwordx4 v[4:5], v[0:3]
	ds_read_b128 v[0:3], v6
	v_lshl_add_u64 v[4:5], v[40:41], 0, v[184:185]
	v_lshl_add_u64 v[4:5], v[42:43], 1, v[4:5]
	v_lshlrev_b32_e32 v184, 1, v59
	v_add3_u32 v6, v46, v76, v77
	s_waitcnt lgkmcnt(0)
	flat_store_dwordx4 v[4:5], v[0:3]
	ds_read_b128 v[0:3], v7
	v_lshl_add_u64 v[4:5], v[40:41], 0, v[184:185]
	v_lshl_add_u64 v[4:5], v[44:45], 1, v[4:5]
	v_lshlrev_b32_e32 v184, 1, v60
	v_ashrrev_i32_e32 v51, 31, v50
	s_waitcnt lgkmcnt(0)
	flat_store_dwordx4 v[4:5], v[0:3]
	ds_read_b128 v[0:3], v8
	v_lshl_add_u64 v[4:5], v[40:41], 0, v[184:185]
	v_lshl_add_u64 v[4:5], v[48:49], 1, v[4:5]
	v_lshlrev_b32_e32 v184, 1, v54
	v_add3_u32 v7, v46, v78, v79
	s_waitcnt lgkmcnt(0)
	flat_store_dwordx4 v[4:5], v[0:3]
	ds_read_b128 v[0:3], v6
	v_lshl_add_u64 v[4:5], v[40:41], 0, v[184:185]
	v_lshl_add_u64 v[4:5], v[50:51], 1, v[4:5]
	v_lshlrev_b32_e32 v184, 1, v61
	v_ashrrev_i32_e32 v53, 31, v52
	s_waitcnt lgkmcnt(0)
	flat_store_dwordx4 v[4:5], v[0:3]
	ds_read_b128 v[0:3], v7
	v_lshl_add_u64 v[4:5], v[40:41], 0, v[184:185]
	v_lshl_add_u64 v[4:5], v[52:53], 1, v[4:5]
	v_add3_u32 v6, v46, v62, v80
	v_lshlrev_b32_e32 v184, 1, v63
	s_waitcnt lgkmcnt(0)
	flat_store_dwordx4 v[4:5], v[0:3]
	ds_read_b128 v[0:3], v6
	v_lshlrev_b32_e32 v6, 3, v55
	v_lshl_add_u64 v[4:5], v[40:41], 0, v[184:185]
	v_ashrrev_i32_e32 v7, 31, v6
	v_lshl_add_u64 v[4:5], v[6:7], 1, v[4:5]
	s_waitcnt lgkmcnt(0)
	flat_store_dwordx4 v[4:5], v[0:3]
	s_waitcnt lgkmcnt(0)
	s_waitcnt lgkmcnt(0)
	s_barrier
	s_cbranch_execnz .LBB0_355
.LBB0_359:
	s_lshl_b32 s2, s54, 16
	s_or_b32 s2, s2, s53
	s_add_u32 s60, s48, s2
	v_mov_b32_e32 v152, v226
	s_addc_u32 s61, s52, 0
	s_lshl_b32 s2, s55, 8
	s_mov_b64 s[62:63], 0xc000
	v_ashrrev_i32_e32 v0, 3, v152
	v_lshrrev_b32_e32 v1, 4, v152
	v_xor_b32_e32 v1, v1, v152
	v_add_u32_e32 v2, s2, v0
	v_ashrrev_i32_e32 v3, 31, v2
	v_lshlrev_b32_e32 v1, 4, v1
	v_lshlrev_b32_e32 v156, 4, v152
	v_lshlrev_b64 v[2:3], 8, v[2:3]
	v_and_b32_e32 v184, 0x70, v1
	v_ashrrev_i32_e32 v1, 31, v0
	v_add_u32_e32 v148, 0, v156
	v_lshl_add_u64 v[2:3], s[16:17], 0, v[2:3]
	v_lshlrev_b64 v[0:1], 8, v[0:1]
	v_readfirstlane_b32 s3, v148
	v_add_u32_e32 v5, 0x2000, v148
	v_lshl_add_u64 v[128:129], v[2:3], 0, v[184:185]
	v_lshl_add_u64 v[0:1], s[60:61], 0, v[0:1]
	s_mov_b32 m0, s3
	s_mov_b64 s[60:61], 0x4000
	v_readfirstlane_b32 s3, v5
	v_add_u32_e32 v5, 0x4000, v148
	global_load_lds_dwordx4 v[128:129], off
	v_lshl_add_u64 v[2:3], v[128:129], 0, s[60:61]
	s_mov_b32 m0, s3
	v_readfirstlane_b32 s3, v5
	v_add_u32_e32 v5, 0x6000, v148
	global_load_lds_dwordx4 v[2:3], off
	v_lshl_add_u64 v[2:3], v[128:129], 0, s[40:41]
	s_mov_b32 m0, s3
	v_readfirstlane_b32 s3, v5
	global_load_lds_dwordx4 v[2:3], off
	v_lshl_add_u64 v[2:3], v[128:129], 0, s[62:63]
	s_mov_b32 m0, s3
	s_add_i32 s3, 0, 0x10000
	global_load_lds_dwordx4 v[2:3], off
	v_add_u32_e32 v2, s3, v156
	v_add_u32_e32 v3, 0x2000, v2
	v_readfirstlane_b32 s22, v2
	v_lshl_add_u64 v[130:131], v[0:1], 0, v[184:185]
	s_mov_b32 m0, s22
	v_readfirstlane_b32 s22, v3
	v_add_u32_e32 v3, 0x4000, v2
	global_load_lds_dwordx4 v[130:131], off
	v_lshl_add_u64 v[0:1], v[130:131], 0, s[60:61]
	s_mov_b32 m0, s22
	v_readfirstlane_b32 s22, v3
	v_add_u32_e32 v2, 0x6000, v2
	global_load_lds_dwordx4 v[0:1], off
	v_lshl_add_u64 v[0:1], v[130:131], 0, s[40:41]
	s_mov_b32 m0, s22
	v_readfirstlane_b32 s22, v2
	v_and_b32_e32 v154, 31, v152
	global_load_lds_dwordx4 v[0:1], off
	v_lshl_add_u64 v[0:1], v[130:131], 0, s[62:63]
	s_mov_b32 m0, s22
	v_add_u32_e32 v5, 0x8000, v148
	global_load_lds_dwordx4 v[0:1], off
	v_lshlrev_b32_e32 v1, 7, v154
	v_add_u32_e32 v153, s3, v1
	s_add_i32 s3, 0, 0x18000
	v_ashrrev_i32_e32 v149, 6, v152
	v_add_u32_e32 v157, s3, v156
	v_readfirstlane_b32 s3, v5
	v_lshlrev_b32_e32 v0, 12, v149
	v_lshl_add_u64 v[2:3], v[128:129], 0, s[30:31]
	s_mov_b32 m0, s3
	v_readfirstlane_b32 s3, v157
	s_waitcnt vmcnt(0)
	s_waitcnt vmcnt(0) lgkmcnt(0)
	s_barrier
; #define SBAR() __builtin_amdgcn_sched_barrier(0)
; DEV void glds16(const u16* g, char* l) { __builtin_amdgcn_global_load_lds((const unsigned*)g, (unsigned*)l, 16, 0, 0); }
; template <int WM, int WN, int BN, int EPI>
; DEV void gemm_tile(const u16* __restrict__ A, int lda, const u16* __restrict__ Bt, int ldb, int K, int m0, char* lds,
;                    const Params& P, int layer, int batch, int nt) {
;     ...
;   for (int kt = 0; kt < nk; ++kt) {
;     const bool more = kt + 1 < nk;
;     const int nb = (kt + 1) & 1;
;     const char* as = As + (kt & 1) * 32768; const char* bs = Bs + (kt & 1) * 32768;
; #pragma unroll
;     for (int ks = 0; ks < 4; ++ks) {
;       if (more) { glds16(Ap + (long)ks * 64 * lda + (kt + 1) * 64, As + nb * 32768 + soff + ks * 8192);
;                   if (ks < NB) glds16(Bp + (long)ks * 64 * ldb + (kt + 1) * 64, Bs + nb * 32768 + soff + ks * 8192); }
;       SBAR();
;       bf16x8 xf[MI], wf[NI];
; #pragma unroll
;       for (int mi = 0; mi < MI; ++mi) xf[mi] = *reinterpret_cast<const bf16x8*>(as + swz128(wm * (MI * 32) + mi * 32 + r32, ks * 2 + hi));
; #pragma unroll
;       for (int ni = 0; ni < NI; ++ni) wf[ni] = *reinterpret_cast<const bf16x8*>(bs + swz128(wn * (NI * 32) + ni * 32 + r32, ks * 2 + hi));
; #pragma unroll
;       for (int mi = 0; mi < MI; ++mi)
; #pragma unroll
;         for (int ni = 0; ni < NI; ++ni) acc[mi][ni] = __builtin_amdgcn_mfma_f32_32x32x16_bf16(wf[ni], xf[mi], acc[mi][ni], 0, 0, 0);
;     }
;     asm volatile("s_waitcnt vmcnt(0)" ::: "memory");
;     __syncthreads();
	v_add3_u32 v151, 0, v0, v1
	v_lshl_add_u64 v[0:1], v[130:131], 0, s[30:31]
	global_load_lds_dwordx4 v[2:3], off
	s_mov_b32 m0, s3
	v_lshrrev_b32_e32 v4, 5, v152
	global_load_lds_dwordx4 v[0:1], off
	v_bfe_u32 v155, v152, 5, 1
	v_bfe_u32 v150, v152, 1, 3
	v_bitop3_b32 v0, v4, v150, 1 bitop3:0x6c
	v_lshlrev_b32_e32 v4, 4, v0
	v_add_u32_e32 v158, v153, v4
	ds_read_b128 v[194:197], v158
	v_add_u32_e32 v159, v151, v4
	ds_read_b128 v[198:201], v159
	ds_read_b128 v[202:205], v158 offset:4096
	ds_read_b128 v[206:209], v158 offset:8192
	ds_read_b128 v[210:213], v158 offset:12288
	ds_read_b128 v[214:217], v158 offset:16384
	ds_read_b128 v[218:221], v158 offset:20480
	ds_read_b128 v[222:225], v158 offset:24576
	ds_read_b128 v[232:235], v158 offset:28672
	v_add_u32_e32 v133, 0xa000, v148
	s_mov_b64 s[60:61], 0x4080
	v_add_u32_e32 v132, 0x2000, v157
	v_readfirstlane_b32 s3, v133
	v_lshl_add_u64 v[78:79], v[128:129], 0, s[60:61]
	s_mov_b32 m0, s3
	s_waitcnt lgkmcnt(7)
	v_mfma_f32_32x32x16_bf16 v[48:63], v[194:197], v[198:201], 0
	v_readfirstlane_b32 s3, v132
	v_lshl_add_u64 v[76:77], v[130:131], 0, s[60:61]
	s_waitcnt lgkmcnt(5)
	v_mfma_f32_32x32x16_bf16 v[32:47], v[202:205], v[198:201], 0
	s_waitcnt lgkmcnt(3)
	v_mfma_f32_32x32x16_bf16 v[112:127], v[214:217], v[198:201], 0
	s_waitcnt lgkmcnt(1)
	v_mfma_f32_32x32x16_bf16 v[96:111], v[218:221], v[198:201], 0
	global_load_lds_dwordx4 v[78:79], off
	s_mov_b32 m0, s3
	s_nop 0
	global_load_lds_dwordx4 v[76:77], off
	v_mfma_f32_32x32x16_bf16 v[16:31], v[206:209], v[198:201], 0
	v_mfma_f32_32x32x16_bf16 v[0:15], v[210:213], v[198:201], 0
	v_mfma_f32_32x32x16_bf16 v[80:95], v[222:225], v[198:201], 0
	s_waitcnt lgkmcnt(0)
	v_mfma_f32_32x32x16_bf16 v[64:79], v[232:235], v[198:201], 0
	v_bitop3_b32 v132, v155, v150, 2 bitop3:0x36
	v_lshlrev_b32_e32 v136, 4, v132
	v_add_u32_e32 v160, v153, v136
	ds_read_b128 v[236:239], v160
	v_add_u32_e32 v161, v151, v136
	ds_read_b128 v[240:243], v161
	ds_read_b128 v[244:247], v160 offset:4096
	ds_read_b128 v[248:251], v160 offset:8192
	ds_read_b128 v[170:173], v160 offset:12288
	ds_read_b128 v[174:177], v160 offset:16384
	ds_read_b128 v[178:181], v160 offset:20480
	ds_read_b128 v[194:197], v160 offset:24576
	ds_read_b128 v[198:201], v160 offset:28672
	v_add_u32_e32 v163, 0xc000, v148
	v_add_u32_e32 v162, 0x4000, v157
	v_readfirstlane_b32 s3, v163
	v_lshl_add_u64 v[146:147], v[128:129], 0, s[42:43]
	s_mov_b32 m0, s3
	v_readfirstlane_b32 s3, v162
	s_waitcnt lgkmcnt(7)
	v_mfma_f32_32x32x16_bf16 v[48:63], v[236:239], v[240:243], v[48:63]
	v_lshl_add_u64 v[144:145], v[130:131], 0, s[42:43]
	s_waitcnt lgkmcnt(5)
	v_mfma_f32_32x32x16_bf16 v[32:47], v[244:247], v[240:243], v[32:47]
	v_mfma_f32_32x32x16_bf16 v[16:31], v[248:251], v[240:243], v[16:31]
	s_waitcnt lgkmcnt(3)
	v_mfma_f32_32x32x16_bf16 v[0:15], v[170:173], v[240:243], v[0:15]
	v_mfma_f32_32x32x16_bf16 v[112:127], v[174:177], v[240:243], v[112:127]
	s_waitcnt lgkmcnt(1)
	v_mfma_f32_32x32x16_bf16 v[96:111], v[178:181], v[240:243], v[96:111]
	global_load_lds_dwordx4 v[146:147], off
	s_mov_b32 m0, s3
	s_nop 0
	global_load_lds_dwordx4 v[144:145], off
	v_mfma_f32_32x32x16_bf16 v[80:95], v[194:197], v[240:243], v[80:95]
	s_waitcnt lgkmcnt(0)
	v_mfma_f32_32x32x16_bf16 v[64:79], v[198:201], v[240:243], v[64:79]
	v_bitop3_b32 v132, v155, v150, 4 bitop3:0x36
	v_lshlrev_b32_e32 v136, 4, v132
	v_add_u32_e32 v144, v153, v136
	ds_read_b128 v[202:205], v144
	v_add_u32_e32 v145, v151, v136
	ds_read_b128 v[206:209], v145
	ds_read_b128 v[210:213], v144 offset:4096
	ds_read_b128 v[214:217], v144 offset:8192
	ds_read_b128 v[218:221], v144 offset:12288
	ds_read_b128 v[222:225], v144 offset:16384
	ds_read_b128 v[232:235], v144 offset:20480
	ds_read_b128 v[236:239], v144 offset:24576
	ds_read_b128 v[240:243], v144 offset:28672
	v_add_u32_e32 v147, 0xe000, v148
	s_mov_b64 s[60:61], 0xc080
	v_add_u32_e32 v146, 0x6000, v157
	v_readfirstlane_b32 s3, v147
	v_lshl_add_u64 v[128:129], v[128:129], 0, s[60:61]
	s_mov_b32 m0, s3
	s_waitcnt lgkmcnt(7)
	v_mfma_f32_32x32x16_bf16 v[48:63], v[202:205], v[206:209], v[48:63]
	v_readfirstlane_b32 s3, v146
	v_lshl_add_u64 v[130:131], v[130:131], 0, s[60:61]
	s_waitcnt lgkmcnt(5)
	v_mfma_f32_32x32x16_bf16 v[32:47], v[210:213], v[206:209], v[32:47]
	v_mfma_f32_32x32x16_bf16 v[16:31], v[214:217], v[206:209], v[16:31]
	s_waitcnt lgkmcnt(3)
	v_mfma_f32_32x32x16_bf16 v[0:15], v[218:221], v[206:209], v[0:15]
	v_mfma_f32_32x32x16_bf16 v[112:127], v[222:225], v[206:209], v[112:127]
	s_waitcnt lgkmcnt(1)
	v_mfma_f32_32x32x16_bf16 v[96:111], v[232:235], v[206:209], v[96:111]
	global_load_lds_dwordx4 v[128:129], off
	s_mov_b32 m0, s3
	s_nop 0
	global_load_lds_dwordx4 v[130:131], off
	v_mfma_f32_32x32x16_bf16 v[80:95], v[236:239], v[206:209], v[80:95]
	s_waitcnt lgkmcnt(0)
	v_mfma_f32_32x32x16_bf16 v[64:79], v[240:243], v[206:209], v[64:79]
	v_bitop3_b32 v128, v155, v150, 6 bitop3:0x36
	v_lshlrev_b32_e32 v132, 4, v128
	v_add_u32_e32 v148, v153, v132
	ds_read_b128 v[244:247], v148
	v_add_u32_e32 v140, v151, v132
	ds_read_b128 v[248:251], v140
	ds_read_b128 v[170:173], v148 offset:4096
	ds_read_b128 v[174:177], v148 offset:8192
	ds_read_b128 v[178:181], v148 offset:12288
	ds_read_b128 v[194:197], v148 offset:16384
	ds_read_b128 v[198:201], v148 offset:20480
	ds_read_b128 v[202:205], v148 offset:24576
	ds_read_b128 v[206:209], v148 offset:28672
	s_waitcnt lgkmcnt(7)
	v_mfma_f32_32x32x16_bf16 v[48:63], v[244:247], v[248:251], v[48:63]
	s_waitcnt lgkmcnt(6)
	v_mfma_f32_32x32x16_bf16 v[32:47], v[170:173], v[248:251], v[32:47]
	s_waitcnt lgkmcnt(5)
	v_mfma_f32_32x32x16_bf16 v[16:31], v[174:177], v[248:251], v[16:31]
	s_waitcnt lgkmcnt(4)
	v_mfma_f32_32x32x16_bf16 v[0:15], v[178:181], v[248:251], v[0:15]
	s_waitcnt lgkmcnt(3)
	v_mfma_f32_32x32x16_bf16 v[112:127], v[194:197], v[248:251], v[112:127]
	s_waitcnt lgkmcnt(2)
	v_mfma_f32_32x32x16_bf16 v[96:111], v[198:201], v[248:251], v[96:111]
	s_waitcnt lgkmcnt(1)
	v_mfma_f32_32x32x16_bf16 v[80:95], v[202:205], v[248:251], v[80:95]
	s_waitcnt vmcnt(0)
	s_waitcnt vmcnt(0) lgkmcnt(0)
	s_barrier
; #define SBAR() __builtin_amdgcn_sched_barrier(0)
;   DEV float* ssq_ckv() const { return (float*)(b + O_SSQCKV); }
; DEV void glds16(const u16* g, char* l) { __builtin_amdgcn_global_load_lds((const unsigned*)g, (unsigned*)l, 16, 0, 0); }
; DEV void epi_ukv(f32x16 (&acc)[1][8], const Params& P, int layer, int batch, int m0, int head, int wid, int r32, int hi, char* lds) {
;   const int t = m0 + wid * 32 + r32;
;   const float rc = __builtin_amdgcn_rsqf((WS{P.ws}.ssq_ckv()[t] + WS{P.ws}.ssq_ckv()[TB + t]) * (1.f / 128.f) + EPS);
;   char* slab = lds + wid * 12800; char* vdst = slab + r32 * 272;
; template <int WM, int WN, int BN, int EPI>
; DEV void gemm_tile(const u16* __restrict__ A, int lda, const u16* __restrict__ Bt, int ldb, int K, int m0, char* lds,
;                    const Params& P, int layer, int batch, int nt) {
;     ...
; #pragma unroll
;     for (int ks = 0; ks < 4; ++ks) {
;       if (more) { glds16(Ap + (long)ks * 64 * lda + (kt + 1) * 64, As + nb * 32768 + soff + ks * 8192);
;                   if (ks < NB) glds16(Bp + (long)ks * 64 * ldb + (kt + 1) * 64, Bs + nb * 32768 + soff + ks * 8192); }
;       SBAR();
;       bf16x8 xf[MI], wf[NI];
; #pragma unroll
;       for (int mi = 0; mi < MI; ++mi) xf[mi] = *reinterpret_cast<const bf16x8*>(as + swz128(wm * (MI * 32) + mi * 32 + r32, ks * 2 + hi));
; #pragma unroll
;       for (int ni = 0; ni < NI; ++ni) wf[ni] = *reinterpret_cast<const bf16x8*>(bs + swz128(wn * (NI * 32) + ni * 32 + r32, ks * 2 + hi));
; #pragma unroll
;       for (int mi = 0; mi < MI; ++mi)
; #pragma unroll
;         for (int ni = 0; ni < NI; ++ni) acc[mi][ni] = __builtin_amdgcn_mfma_f32_32x32x16_bf16(wf[ni], xf[mi], acc[mi][ni], 0, 0, 0);
;     }
;     asm volatile("s_waitcnt vmcnt(0)" ::: "memory");
;     __syncthreads();
	v_mfma_f32_32x32x16_bf16 v[64:79], v[206:209], v[248:251], v[64:79]
	ds_read_b128 v[210:213], v158 offset:32768
	ds_read_b128 v[214:217], v159 offset:32768
	ds_read_b128 v[218:221], v158 offset:36864
	ds_read_b128 v[222:225], v158 offset:40960
	ds_read_b128 v[232:235], v158 offset:45056
	ds_read_b128 v[236:239], v158 offset:49152
	ds_read_b128 v[240:243], v158 offset:53248
	ds_read_b128 v[244:247], v158 offset:57344
	ds_read_b128 v[248:251], v158 offset:61440
	ds_read_b128 v[170:173], v160 offset:32768
	s_waitcnt lgkmcnt(8)
	v_mfma_f32_32x32x16_bf16 v[48:63], v[210:213], v[214:217], v[48:63]
	ds_read_b128 v[174:177], v161 offset:32768
	s_waitcnt lgkmcnt(8)
	v_mfma_f32_32x32x16_bf16 v[32:47], v[218:221], v[214:217], v[32:47]
	ds_read_b128 v[178:181], v160 offset:36864
	s_waitcnt lgkmcnt(8)
	v_mfma_f32_32x32x16_bf16 v[16:31], v[222:225], v[214:217], v[16:31]
	ds_read_b128 v[194:197], v160 offset:40960
	s_waitcnt lgkmcnt(8)
	v_mfma_f32_32x32x16_bf16 v[0:15], v[232:235], v[214:217], v[0:15]
	ds_read_b128 v[198:201], v160 offset:45056
	s_waitcnt lgkmcnt(8)
	v_mfma_f32_32x32x16_bf16 v[112:127], v[236:239], v[214:217], v[112:127]
	ds_read_b128 v[202:205], v160 offset:49152
	s_waitcnt lgkmcnt(8)
	v_mfma_f32_32x32x16_bf16 v[96:111], v[240:243], v[214:217], v[96:111]
	ds_read_b128 v[206:209], v160 offset:53248
	s_waitcnt lgkmcnt(8)
	v_mfma_f32_32x32x16_bf16 v[80:95], v[244:247], v[214:217], v[80:95]
	ds_read_b128 v[210:213], v160 offset:57344
	s_waitcnt lgkmcnt(8)
	v_mfma_f32_32x32x16_bf16 v[64:79], v[248:251], v[214:217], v[64:79]
	ds_read_b128 v[214:217], v160 offset:61440
	ds_read_b128 v[218:221], v144 offset:32768
	s_waitcnt lgkmcnt(8)
	v_mfma_f32_32x32x16_bf16 v[48:63], v[170:173], v[174:177], v[48:63]
	ds_read_b128 v[222:225], v145 offset:32768
	s_waitcnt lgkmcnt(8)
	v_mfma_f32_32x32x16_bf16 v[32:47], v[178:181], v[174:177], v[32:47]
	ds_read_b128 v[232:235], v144 offset:36864
	s_waitcnt lgkmcnt(8)
	v_mfma_f32_32x32x16_bf16 v[16:31], v[194:197], v[174:177], v[16:31]
	ds_read_b128 v[236:239], v144 offset:40960
	s_waitcnt lgkmcnt(8)
	v_mfma_f32_32x32x16_bf16 v[0:15], v[198:201], v[174:177], v[0:15]
	ds_read_b128 v[240:243], v144 offset:45056
	s_waitcnt lgkmcnt(8)
	v_mfma_f32_32x32x16_bf16 v[112:127], v[202:205], v[174:177], v[112:127]
	ds_read_b128 v[244:247], v144 offset:49152
	s_waitcnt lgkmcnt(8)
	v_mfma_f32_32x32x16_bf16 v[96:111], v[206:209], v[174:177], v[96:111]
	ds_read_b128 v[248:251], v144 offset:53248
	s_waitcnt lgkmcnt(8)
	v_mfma_f32_32x32x16_bf16 v[80:95], v[210:213], v[174:177], v[80:95]
	ds_read_b128 v[170:173], v144 offset:57344
	s_waitcnt lgkmcnt(8)
	v_mfma_f32_32x32x16_bf16 v[64:79], v[214:217], v[174:177], v[64:79]
	ds_read_b128 v[174:177], v144 offset:61440
	ds_read_b128 v[178:181], v148 offset:49152
	s_waitcnt lgkmcnt(8)
	v_mfma_f32_32x32x16_bf16 v[48:63], v[218:221], v[222:225], v[48:63]
	ds_read_b128 v[194:197], v140 offset:32768
	s_waitcnt lgkmcnt(8)
	v_mfma_f32_32x32x16_bf16 v[32:47], v[232:235], v[222:225], v[32:47]
	ds_read_b128 v[198:201], v148 offset:45056
	s_waitcnt lgkmcnt(8)
	v_mfma_f32_32x32x16_bf16 v[16:31], v[236:239], v[222:225], v[16:31]
	ds_read_b128 v[202:205], v148 offset:32768
	s_waitcnt lgkmcnt(8)
	v_mfma_f32_32x32x16_bf16 v[0:15], v[240:243], v[222:225], v[0:15]
	ds_read_b128 v[206:209], v148 offset:53248
	s_waitcnt lgkmcnt(8)
	v_mfma_f32_32x32x16_bf16 v[112:127], v[244:247], v[222:225], v[112:127]
	s_waitcnt lgkmcnt(7)
	v_mfma_f32_32x32x16_bf16 v[96:111], v[248:251], v[222:225], v[96:111]
	s_waitcnt lgkmcnt(6)
	v_mfma_f32_32x32x16_bf16 v[80:95], v[170:173], v[222:225], v[80:95]
	s_waitcnt lgkmcnt(5)
	v_mfma_f32_32x32x16_bf16 v[64:79], v[174:177], v[222:225], v[64:79]
	v_lshlrev_b32_e32 v157, 3, v155
	s_waitcnt lgkmcnt(3)
	v_mfma_f32_32x32x16_bf16 v[112:127], v[178:181], v[194:197], v[112:127]
	ds_read_b128 v[144:147], v148 offset:36864
	ds_read_b128 v[136:139], v148 offset:40960
	ds_read_b128 v[162:165], v148 offset:57344
	ds_read_b128 v[166:169], v148 offset:61440
	v_lshl_add_u32 v148, v149, 5, s2
	v_or_b32_e32 v150, v148, v154
	v_ashrrev_i32_e32 v151, 31, v150
	s_waitcnt vmcnt(0)
	s_waitcnt lgkmcnt(0)
	s_barrier
	v_mfma_f32_32x32x16_bf16 v[96:111], v[206:209], v[194:197], v[96:111]
	v_lshl_add_u64 v[158:159], v[150:151], 2, s[18:19]
	v_add_co_u32_e32 v160, vcc, s93, v158
	s_nop 1
	v_addc_co_u32_e32 v161, vcc, 0, v159, vcc
	flat_load_dword v153, v[158:159]
	s_nop 0
	flat_load_dword v158, v[160:161]
	v_mfma_f32_32x32x16_bf16 v[80:95], v[162:165], v[194:197], v[80:95]
	v_mul_lo_u32 v149, v149, s99
	v_mul_u32_u24_e32 v159, 0x110, v154
	v_and_b32_e32 v184, 0xf0, v156
	s_lshl_b32 s22, s54, 8
	s_movk_i32 s2, 0xfff
	s_waitcnt vmcnt(0) lgkmcnt(0)
;   DEV u16* VB() const { return (u16*)(b + O_VB); }
;   DEV float* ssq_ckv() const { return (float*)(b + O_SSQCKV); }
; #define LDSP(T) __attribute__((address_space(3))) T*
; template <int NCH, int STRIDE> DEV void slab_flush(char* slab, u16* grow0, int gstride, int lane) {
;   asm volatile("s_waitcnt lgkmcnt(0)" ::: "memory");
; #pragma unroll
;   for (int i = 0; i < NCH / 2; ++i) {
;     const int q = i * 64 + lane, row = q / NCH, cc = q - row * NCH;
;     const u32x4 v = *(LDSP(const u32x4))(slab + row * STRIDE + cc * 16);
;     *reinterpret_cast<u32x4*>(grow0 + (long)row * gstride + cc * 8) = v;
;   }
;   asm volatile("s_waitcnt lgkmcnt(0)" ::: "memory");
; }
; DEV void epi_ukv(f32x16 (&acc)[1][8], const Params& P, int layer, int batch, int m0, int head, int wid, int r32, int hi, char* lds) {
;   const int t = m0 + wid * 32 + r32;
;   const float rc = __builtin_amdgcn_rsqf((WS{P.ws}.ssq_ckv()[t] + WS{P.ws}.ssq_ckv()[TB + t]) * (1.f / 128.f) + EPS);
;   char* slab = lds + wid * 12800; char* vdst = slab + r32 * 272;
; #pragma unroll
;   for (int ni = 4; ni < 8; ++ni)
; #pragma unroll
;     for (int r4 = 0; r4 < 4; ++r4) {
;       const f32x16& a = acc[0][ni];
;       st4lds(vdst, (ni - 4) * 32 + r4 * 8 + hi * 4, a[r4 * 4] * rc, a[r4 * 4 + 1] * rc, a[r4 * 4 + 2] * rc, a[r4 * 4 + 3] * rc);
;     }
;   slab_flush<16, 272>(slab, WS{P.ws}.VB() + (long)(m0 + wid * 32) * 512 + head * 128, 512, hi * 32 + r32);
	v_add_f32_e32 v153, v153, v158
	v_fmamk_f32 v153, v153, 0x3c000000, v227
	v_rsq_f32_e32 v158, v153
	v_add_u32_e32 v153, 0, v149
	v_add3_u32 v149, v153, v159, v157
	v_mfma_f32_32x32x16_bf16 v[64:79], v[166:169], v[194:197], v[64:79]
	v_mul_f32_e32 v112, v112, v158
	v_mul_f32_e32 v113, v113, v158
	v_mul_f32_e32 v114, v114, v158
	v_mul_f32_e32 v115, v115, v158
	v_mul_f32_e32 v159, v80, v158
	v_mul_f32_e32 v160, v81, v158
	v_cvt_pk_bf16_f32 v80, v112, v113
	v_cvt_pk_bf16_f32 v81, v114, v115
	v_mul_f32_e32 v116, v116, v158
	v_mul_f32_e32 v117, v117, v158
	v_mul_f32_e32 v118, v118, v158
	v_mul_f32_e32 v119, v119, v158
	ds_write_b64 v149, v[80:81]
	v_cvt_pk_bf16_f32 v80, v116, v117
	v_cvt_pk_bf16_f32 v81, v118, v119
	v_mul_f32_e32 v120, v120, v158
	v_mul_f32_e32 v121, v121, v158
	v_mul_f32_e32 v122, v122, v158
	v_mul_f32_e32 v123, v123, v158
	ds_write_b64 v149, v[80:81] offset:16
	v_cvt_pk_bf16_f32 v80, v120, v121
	v_cvt_pk_bf16_f32 v81, v122, v123
	v_mul_f32_e32 v124, v124, v158
	v_mul_f32_e32 v125, v125, v158
	v_mul_f32_e32 v126, v126, v158
	v_mul_f32_e32 v127, v127, v158
	ds_write_b64 v149, v[80:81] offset:32
	v_cvt_pk_bf16_f32 v80, v124, v125
	v_cvt_pk_bf16_f32 v81, v126, v127
	v_mul_f32_e32 v96, v96, v158
	v_mul_f32_e32 v97, v97, v158
	v_mul_f32_e32 v98, v98, v158
	v_mul_f32_e32 v99, v99, v158
	ds_write_b64 v149, v[80:81] offset:48
	v_cvt_pk_bf16_f32 v80, v96, v97
	v_cvt_pk_bf16_f32 v81, v98, v99
	v_mul_f32_e32 v100, v100, v158
	v_mul_f32_e32 v101, v101, v158
	v_mul_f32_e32 v102, v102, v158
	v_mul_f32_e32 v103, v103, v158
	ds_write_b64 v149, v[80:81] offset:64
	v_cvt_pk_bf16_f32 v80, v100, v101
	v_cvt_pk_bf16_f32 v81, v102, v103
	v_mul_f32_e32 v104, v104, v158
	v_mul_f32_e32 v105, v105, v158
	v_mul_f32_e32 v106, v106, v158
	v_mul_f32_e32 v107, v107, v158
	ds_write_b64 v149, v[80:81] offset:80
	v_cvt_pk_bf16_f32 v80, v104, v105
	v_cvt_pk_bf16_f32 v81, v106, v107
	v_mul_f32_e32 v108, v108, v158
	v_mul_f32_e32 v109, v109, v158
	v_mul_f32_e32 v110, v110, v158
	v_mul_f32_e32 v111, v111, v158
	ds_write_b64 v149, v[80:81] offset:96
	v_cvt_pk_bf16_f32 v80, v108, v109
	v_cvt_pk_bf16_f32 v81, v110, v111
	v_mul_f32_e32 v82, v82, v158
	v_mul_f32_e32 v83, v83, v158
	ds_write_b64 v149, v[80:81] offset:112
	v_cvt_pk_bf16_f32 v80, v159, v160
	v_cvt_pk_bf16_f32 v81, v82, v83
	v_mul_f32_e32 v84, v84, v158
	v_mul_f32_e32 v85, v85, v158
	v_mul_f32_e32 v86, v86, v158
	v_mul_f32_e32 v87, v87, v158
	ds_write_b64 v149, v[80:81] offset:128
	v_cvt_pk_bf16_f32 v80, v84, v85
	v_cvt_pk_bf16_f32 v81, v86, v87
	ds_write_b64 v149, v[80:81] offset:144
	v_mul_f32_e32 v80, v88, v158
	v_mul_f32_e32 v81, v89, v158
	v_mul_f32_e32 v82, v90, v158
	v_mul_f32_e32 v83, v91, v158
	v_cvt_pk_bf16_f32 v80, v80, v81
	v_cvt_pk_bf16_f32 v81, v82, v83
	ds_write_b64 v149, v[80:81] offset:160
	v_mul_f32_e32 v80, v92, v158
	v_mul_f32_e32 v81, v93, v158
	v_mul_f32_e32 v64, v64, v158
	v_mul_f32_e32 v65, v65, v158
	v_mul_f32_e32 v82, v94, v158
	v_mul_f32_e32 v83, v95, v158
	v_cvt_pk_bf16_f32 v80, v80, v81
	v_cvt_pk_bf16_f32 v81, v82, v83
	ds_write_b64 v149, v[80:81] offset:176
	v_mul_f32_e32 v66, v66, v158
	v_mul_f32_e32 v67, v67, v158
	v_cvt_pk_bf16_f32 v64, v64, v65
	v_cvt_pk_bf16_f32 v65, v66, v67
	ds_write_b64 v149, v[64:65] offset:192
	v_mul_f32_e32 v64, v68, v158
	v_mul_f32_e32 v65, v69, v158
	v_mul_f32_e32 v66, v70, v158
	v_mul_f32_e32 v67, v71, v158
	v_cvt_pk_bf16_f32 v64, v64, v65
	v_cvt_pk_bf16_f32 v65, v66, v67
	ds_write_b64 v149, v[64:65] offset:208
	v_mul_f32_e32 v64, v72, v158
	v_mul_f32_e32 v65, v73, v158
	v_mul_f32_e32 v66, v74, v158
	v_mul_f32_e32 v67, v75, v158
	v_cvt_pk_bf16_f32 v64, v64, v65
	v_cvt_pk_bf16_f32 v65, v66, v67
	ds_write_b64 v149, v[64:65] offset:224
	v_mul_f32_e32 v64, v76, v158
	v_mul_f32_e32 v65, v77, v158
	v_mul_f32_e32 v66, v78, v158
	v_mul_f32_e32 v67, v79, v158
	v_cvt_pk_bf16_f32 v64, v64, v65
	v_cvt_pk_bf16_f32 v65, v66, v67
	ds_write_b64 v149, v[64:65] offset:240
	v_ashrrev_i32_e32 v149, 31, v148
	v_lshlrev_b64 v[64:65], 10, v[148:149]
	v_bfe_u32 v70, v152, 4, 2
	v_lshl_add_u64 v[68:69], s[24:25], 0, v[64:65]
	v_mul_u32_u24_e32 v64, 0x110, v70
	s_waitcnt lgkmcnt(0)
	v_add3_u32 v72, v153, v184, v64
	ds_read_b128 v[64:67], v72
	v_lshl_add_u64 v[68:69], v[68:69], 0, s[22:23]
	v_lshl_add_u64 v[68:69], v[68:69], 0, v[184:185]
	v_lshlrev_b32_e32 v184, 10, v70
	v_lshl_add_u64 v[70:71], v[68:69], 0, v[184:185]
	s_waitcnt lgkmcnt(0)
	flat_store_dwordx4 v[70:71], v[64:67]
	ds_read_b128 v[64:67], v72 offset:1088
	v_or_b32_e32 v70, 0x1000, v184
	v_mov_b32_e32 v71, v185
	v_lshl_add_u64 v[70:71], v[68:69], 0, v[70:71]
	v_mfma_f32_32x32x16_bf16 v[32:47], v[144:147], v[194:197], v[32:47]
	s_waitcnt lgkmcnt(0)
	flat_store_dwordx4 v[70:71], v[64:67]
	ds_read_b128 v[64:67], v72 offset:2176
	v_or_b32_e32 v70, 0x2000, v184
	v_mov_b32_e32 v71, v185
	v_lshl_add_u64 v[70:71], v[68:69], 0, v[70:71]
	s_mul_i32 s22, s54, 0x180
	s_waitcnt lgkmcnt(0)
	flat_store_dwordx4 v[70:71], v[64:67]
	ds_read_b128 v[64:67], v72 offset:3264
	v_or_b32_e32 v70, 0x3000, v184
	v_mov_b32_e32 v71, v185
	v_lshl_add_u64 v[70:71], v[68:69], 0, v[70:71]
	v_mfma_f32_32x32x16_bf16 v[48:63], v[202:205], v[194:197], v[48:63]
	s_waitcnt lgkmcnt(0)
	flat_store_dwordx4 v[70:71], v[64:67]
	ds_read_b128 v[64:67], v72 offset:4352
	v_or_b32_e32 v70, 0x4000, v184
	v_mov_b32_e32 v71, v185
	v_lshl_add_u64 v[70:71], v[68:69], 0, v[70:71]
	v_mul_f32_e32 v75, v32, v158
	s_waitcnt lgkmcnt(0)
	flat_store_dwordx4 v[70:71], v[64:67]
	ds_read_b128 v[64:67], v72 offset:5440
	v_or_b32_e32 v70, 0x5000, v184
	v_mov_b32_e32 v71, v185
	v_lshl_add_u64 v[70:71], v[68:69], 0, v[70:71]
	v_mul_f32_e32 v76, v33, v158
	s_waitcnt lgkmcnt(0)
; DEV void epi_ukv(f32x16 (&acc)[1][8], const Params& P, int layer, int batch, int m0, int head, int wid, int r32, int hi, char* lds) {
;     ...
;   float s = 0.f;
; #pragma unroll
;   for (int ni = 0; ni < 4; ++ni)
; #pragma unroll
;     for (int r = 0; r < 16; ++r) { acc[0][ni][r] *= rc; s += acc[0][ni][r] * acc[0][ni][r]; }
;   float4 kr[2][4];
; #pragma unroll
;   for (int b = 0; b < 2; ++b)
; #pragma unroll
;     for (int r4 = 0; r4 < 4; ++r4) {
;       kr[b][r4] = *reinterpret_cast<const float4*>(WS{P.ws}.KR() + (long)t * 64 + b * 32 + r4 * 8 + hi * 4);
;       s += kr[b][r4].x * kr[b][r4].x + kr[b][r4].y * kr[b][r4].y + kr[b][r4].z * kr[b][r4].z + kr[b][r4].w * kr[b][r4].w;
;     }
;   s = swapsum(s);
;   const float inv = __builtin_amdgcn_rsqf(s * (1.f / 192.f) + EPS);
;   const float* g = WS{P.ws}.consts() + layer * 1024 + 512;
;   char* dst = slab + r32 * 400;
; #pragma unroll
;   for (int ni = 0; ni < 4; ++ni)
; #pragma unroll
;     for (int r4 = 0; r4 < 4; ++r4) {
;       const int c = ni * 32 + r4 * 8 + hi * 4;
;       const float4 gg = *reinterpret_cast<const float4*>(g + c);
	flat_store_dwordx4 v[70:71], v[64:67]
	ds_read_b128 v[64:67], v72 offset:6528
	v_or_b32_e32 v70, 0x6000, v184
	v_mov_b32_e32 v71, v185
	v_lshl_add_u64 v[70:71], v[68:69], 0, v[70:71]
	v_or_b32_e32 v184, 0x7000, v184
	s_waitcnt lgkmcnt(0)
	flat_store_dwordx4 v[70:71], v[64:67]
	ds_read_b128 v[64:67], v72 offset:7616
	v_lshl_add_u64 v[68:69], v[68:69], 0, v[184:185]
	v_lshlrev_b64 v[32:33], 8, v[150:151]
	v_lshl_add_u64 v[32:33], s[68:69], 0, v[32:33]
	v_lshlrev_b32_e32 v184, 4, v155
	s_waitcnt lgkmcnt(0)
	flat_store_dwordx4 v[68:69], v[64:67]
	s_waitcnt lgkmcnt(0)
	v_mul_f32_e32 v73, v56, v158
	v_mul_f32_e32 v74, v57, v158
	v_lshl_add_u64 v[56:57], v[32:33], 0, v[184:185]
	v_mul_f32_e32 v64, v48, v158
	v_mul_f32_e32 v65, v49, v158
	v_mul_f32_e32 v67, v50, v158
	v_mul_f32_e32 v68, v51, v158
	flat_load_dwordx4 v[48:51], v[56:57]
	v_mul_f32_e32 v83, v40, v158
	v_mul_f32_e32 v84, v41, v158
	v_mul_f32_e32 v85, v42, v158
	v_mul_f32_e32 v86, v43, v158
	flat_load_dwordx4 v[40:43], v[56:57] offset:32
	v_mul_f32_e32 v79, v36, v158
	v_mul_f32_e32 v80, v37, v158
	v_mul_f32_e32 v81, v38, v158
	v_mul_f32_e32 v82, v39, v158
	flat_load_dwordx4 v[36:39], v[56:57] offset:64
	v_mfma_f32_32x32x16_bf16 v[16:31], v[136:139], v[194:197], v[16:31]
	v_mul_f32_e32 v77, v34, v158
	v_mul_f32_e32 v78, v35, v158
	flat_load_dwordx4 v[32:35], v[56:57] offset:96
	v_mul_f32_e32 v69, v52, v158
	v_mul_f32_e32 v70, v53, v158
	v_mul_f32_e32 v71, v54, v158
	v_mul_f32_e32 v72, v55, v158
	v_mul_f32_e32 v87, v44, v158
	v_mul_f32_e32 v88, v45, v158
	v_mul_f32_e32 v89, v46, v158
	v_mul_f32_e32 v90, v47, v158
	flat_load_dwordx4 v[52:55], v[56:57] offset:128
	flat_load_dwordx4 v[44:47], v[56:57] offset:160
	v_mul_f32_e32 v91, v16, v158
	v_mul_f32_e32 v92, v17, v158
	v_mul_f32_e32 v93, v18, v158
	v_mul_f32_e32 v94, v19, v158
	v_mul_f32_e32 v95, v20, v158
	v_mul_f32_e32 v96, v21, v158
	v_mul_f32_e32 v97, v22, v158
	v_mul_f32_e32 v98, v23, v158
	flat_load_dwordx4 v[20:23], v[56:57] offset:192
	flat_load_dwordx4 v[16:19], v[56:57] offset:224
	v_mul_f32_e32 v66, v65, v65
	v_fmac_f32_e32 v66, v64, v64
	v_fmac_f32_e32 v66, v67, v67
	v_fmac_f32_e32 v66, v68, v68
	v_fmac_f32_e32 v66, v69, v69
	v_mfma_f32_32x32x16_bf16 v[0:15], v[198:201], v[194:197], v[0:15]
	v_fmac_f32_e32 v66, v70, v70
	v_fmac_f32_e32 v66, v71, v71
	v_fmac_f32_e32 v66, v72, v72
	v_fmac_f32_e32 v66, v73, v73
	v_fmac_f32_e32 v66, v74, v74
	v_mul_f32_e32 v58, v58, v158
	v_fmac_f32_e32 v66, v58, v58
	v_mul_f32_e32 v59, v59, v158
	v_fmac_f32_e32 v66, v59, v59
	v_mul_f32_e32 v60, v60, v158
	v_fmac_f32_e32 v66, v60, v60
	v_mul_f32_e32 v61, v61, v158
	v_mul_f32_e32 v101, v26, v158
	v_mul_f32_e32 v56, v27, v158
	v_lshl_add_u64 v[26:27], s[10:11], 0, v[184:185]
	v_fmac_f32_e32 v66, v61, v61
	v_mul_f32_e32 v62, v62, v158
	v_mul_f32_e32 v57, v0, v158
	v_mul_f32_e32 v102, v1, v158
	v_mul_f32_e32 v103, v2, v158
	v_mul_f32_e32 v104, v3, v158
	flat_load_dwordx4 v[0:3], v[26:27] offset:2048
	global_load_dwordx4 v[194:197], v[26:27], off offset:2080
	global_load_dwordx4 v[198:201], v[26:27], off offset:2112
	global_load_dwordx4 v[202:205], v[26:27], off offset:2144
	global_load_dwordx4 v[206:209], v[26:27], off offset:2176
	global_load_dwordx4 v[210:213], v[26:27], off offset:2208
	global_load_dwordx4 v[214:217], v[26:27], off offset:2240
	global_load_dwordx4 v[218:221], v[26:27], off offset:2272
	global_load_dwordx4 v[222:225], v[26:27], off offset:2304
	global_load_dwordx4 v[232:235], v[26:27], off offset:2336
	global_load_dwordx4 v[236:239], v[26:27], off offset:2368
	global_load_dwordx4 v[240:243], v[26:27], off offset:2400
	global_load_dwordx4 v[244:247], v[26:27], off offset:2432
	global_load_dwordx4 v[248:251], v[26:27], off offset:2464
	global_load_dwordx4 v[170:173], v[26:27], off offset:2496
	global_load_dwordx4 v[174:177], v[26:27], off offset:2528
	v_fmac_f32_e32 v66, v62, v62
	v_mul_f32_e32 v63, v63, v158
	v_fmac_f32_e32 v66, v63, v63
	v_fmac_f32_e32 v66, v75, v75
	v_fmac_f32_e32 v66, v76, v76
	v_fmac_f32_e32 v66, v77, v77
	v_fmac_f32_e32 v66, v78, v78
	v_fmac_f32_e32 v66, v79, v79
	v_fmac_f32_e32 v66, v80, v80
	v_fmac_f32_e32 v66, v81, v81
	v_fmac_f32_e32 v66, v82, v82
	v_fmac_f32_e32 v66, v83, v83
	v_fmac_f32_e32 v66, v84, v84
	v_fmac_f32_e32 v66, v85, v85
	v_fmac_f32_e32 v66, v86, v86
	v_fmac_f32_e32 v66, v87, v87
	v_fmac_f32_e32 v66, v88, v88
	v_fmac_f32_e32 v66, v89, v89
	v_fmac_f32_e32 v66, v90, v90
	v_fmac_f32_e32 v66, v91, v91
	v_fmac_f32_e32 v66, v92, v92
	v_fmac_f32_e32 v66, v93, v93
	v_fmac_f32_e32 v66, v94, v94
	v_fmac_f32_e32 v66, v95, v95
	v_fmac_f32_e32 v66, v96, v96
	v_fmac_f32_e32 v66, v97, v97
	v_fmac_f32_e32 v66, v98, v98
	v_mul_f32_e32 v99, v24, v158
	v_fmac_f32_e32 v66, v99, v99
	v_mul_f32_e32 v100, v25, v158
	v_fmac_f32_e32 v66, v100, v100
	v_fmac_f32_e32 v66, v101, v101
	v_fmac_f32_e32 v66, v56, v56
	v_mul_f32_e32 v28, v28, v158
	v_fmac_f32_e32 v66, v28, v28
	v_mul_f32_e32 v29, v29, v158
	v_fmac_f32_e32 v66, v29, v29
	v_mul_f32_e32 v30, v30, v158
	v_fmac_f32_e32 v66, v30, v30
	v_mul_f32_e32 v31, v31, v158
	v_fmac_f32_e32 v66, v31, v31
	v_fmac_f32_e32 v66, v57, v57
	v_fmac_f32_e32 v66, v102, v102
	v_fmac_f32_e32 v66, v103, v103
	v_fmac_f32_e32 v66, v104, v104
	v_mul_f32_e32 v105, v4, v158
	v_fmac_f32_e32 v66, v105, v105
	v_mul_f32_e32 v106, v5, v158
	v_fmac_f32_e32 v66, v106, v106
	v_mul_f32_e32 v107, v6, v158
	v_fmac_f32_e32 v66, v107, v107
	v_mul_f32_e32 v108, v7, v158
	v_fmac_f32_e32 v66, v108, v108
	v_mul_f32_e32 v8, v8, v158
	v_fmac_f32_e32 v66, v8, v8
	v_mul_f32_e32 v9, v9, v158
	v_fmac_f32_e32 v66, v9, v9
	v_mul_f32_e32 v10, v10, v158
	v_fmac_f32_e32 v66, v10, v10
	v_mul_f32_e32 v11, v11, v158
	v_fmac_f32_e32 v66, v11, v11
	v_mul_f32_e32 v12, v12, v158
	v_fmac_f32_e32 v66, v12, v12
	v_mul_f32_e32 v13, v13, v158
	s_waitcnt vmcnt(0) lgkmcnt(0)
; DEV void epi_ukv(f32x16 (&acc)[1][8], const Params& P, int layer, int batch, int m0, int head, int wid, int r32, int hi, char* lds) {
;     ...
;       s += kr[b][r4].x * kr[b][r4].x + kr[b][r4].y * kr[b][r4].y + kr[b][r4].z * kr[b][r4].z + kr[b][r4].w * kr[b][r4].w;
;     }
;   s = swapsum(s);
;   const float inv = __builtin_amdgcn_rsqf(s * (1.f / 192.f) + EPS);
;   const float* g = WS{P.ws}.consts() + layer * 1024 + 512;
;   char* dst = slab + r32 * 400;
; #pragma unroll
;   for (int ni = 0; ni < 4; ++ni)
; #pragma unroll
;     for (int r4 = 0; r4 < 4; ++r4) {
;       const int c = ni * 32 + r4 * 8 + hi * 4;
;       const float4 gg = *reinterpret_cast<const float4*>(g + c);
;       const f32x16& a = acc[0][ni];
;       st4lds(dst, c, a[r4 * 4] * inv * gg.x, a[r4 * 4 + 1] * inv * gg.y, a[r4 * 4 + 2] * inv * gg.z, a[r4 * 4 + 3] * inv * gg.w);
;     }
	v_mul_f32_e32 v4, v49, v49
	v_fmac_f32_e32 v66, v13, v13
	v_mul_f32_e32 v14, v14, v158
	v_fmac_f32_e32 v4, v48, v48
	v_mul_f32_e32 v5, v41, v41
	v_fmac_f32_e32 v66, v14, v14
	v_mul_f32_e32 v15, v15, v158
	v_fmac_f32_e32 v4, v50, v50
	v_fmac_f32_e32 v5, v40, v40
	v_fmac_f32_e32 v66, v15, v15
	v_fmac_f32_e32 v4, v51, v51
	v_fmac_f32_e32 v5, v42, v42
	v_add_f32_e32 v4, v66, v4
	v_fmac_f32_e32 v5, v43, v43
	v_add_f32_e32 v4, v4, v5
	v_mul_f32_e32 v5, v37, v37
	v_fmac_f32_e32 v5, v36, v36
	v_fmac_f32_e32 v5, v38, v38
	v_fmac_f32_e32 v5, v39, v39
	v_add_f32_e32 v4, v4, v5
	v_mul_f32_e32 v5, v33, v33
	v_fmac_f32_e32 v5, v32, v32
	v_fmac_f32_e32 v5, v34, v34
	v_fmac_f32_e32 v5, v35, v35
	v_mov_b32_e32 v6, v53
	v_mov_b32_e32 v7, v45
	v_add_f32_e32 v24, v4, v5
	v_mov_b32_e32 v4, v52
	v_mov_b32_e32 v5, v44
	v_pk_mul_f32 v[6:7], v[6:7], v[6:7]
	v_lshlrev_b32_e32 v184, 5, v155
	v_pk_fma_f32 v[4:5], v[4:5], v[4:5], v[6:7]
	v_mov_b32_e32 v6, v54
	v_mov_b32_e32 v7, v46
	v_pk_fma_f32 v[4:5], v[6:7], v[6:7], v[4:5]
	v_mov_b32_e32 v6, v55
	v_mov_b32_e32 v7, v47
	v_pk_fma_f32 v[4:5], v[6:7], v[6:7], v[4:5]
	v_mov_b32_e32 v6, v21
	v_add_f32_e32 v4, v24, v4
	v_mov_b32_e32 v7, v17
	v_add_f32_e32 v24, v4, v5
	v_mov_b32_e32 v4, v20
	v_mov_b32_e32 v5, v16
	v_pk_mul_f32 v[6:7], v[6:7], v[6:7]
	s_nop 0
	v_pk_fma_f32 v[4:5], v[4:5], v[4:5], v[6:7]
	v_mov_b32_e32 v6, v22
	v_mov_b32_e32 v7, v18
	v_pk_fma_f32 v[4:5], v[6:7], v[6:7], v[4:5]
	v_mov_b32_e32 v6, v23
	v_mov_b32_e32 v7, v19
	v_pk_fma_f32 v[4:5], v[6:7], v[6:7], v[4:5]
	s_nop 0
	v_add_f32_e32 v4, v24, v4
	v_add_f32_e32 v4, v4, v5
	v_mov_b32_e32 v5, v4
	s_nop 1
	v_permlane32_swap_b32_e32 v4, v5
	v_add_f32_e32 v4, v4, v5
	v_fmamk_f32 v4, v4, 0x3baaaaab, v227
	v_rsq_f32_e32 v24, v4
	v_mul_u32_u24_e32 v4, 0x190, v154
	v_add3_u32 v25, v153, v4, v157
	v_mul_f32_e32 v5, v64, v24
	v_mul_f32_e32 v0, v0, v5
	v_mul_f32_e32 v5, v65, v24
	v_mul_f32_e32 v1, v1, v5
	v_mul_f32_e32 v5, v67, v24
	v_mul_f32_e32 v2, v2, v5
	v_mul_f32_e32 v5, v68, v24
	v_mul_f32_e32 v3, v3, v5
	v_cvt_pk_bf16_f32 v0, v0, v1
	v_cvt_pk_bf16_f32 v1, v2, v3
	ds_write_b64 v25, v[0:1]
	v_mul_f32_e32 v4, v69, v24
	v_mul_f32_e32 v5, v74, v24
	v_mul_f32_e32 v6, v62, v24
	v_mul_f32_e32 v7, v63, v24
	s_waitcnt vmcnt(0) lgkmcnt(0)
	v_mul_f32_e32 v0, v4, v194
	v_mul_f32_e32 v4, v70, v24
	v_mul_f32_e32 v1, v4, v195
	v_mul_f32_e32 v4, v71, v24
	v_mul_f32_e32 v2, v4, v196
	v_mul_f32_e32 v4, v72, v24
	v_mul_f32_e32 v3, v4, v197
	v_cvt_pk_bf16_f32 v0, v0, v1
	v_cvt_pk_bf16_f32 v1, v2, v3
	ds_write_b64 v25, v[0:1] offset:16
	v_mul_f32_e32 v4, v73, v24
	s_waitcnt vmcnt(0) lgkmcnt(0)
	v_mul_f32_e32 v0, v4, v198
	v_mul_f32_e32 v4, v58, v24
	v_mul_f32_e32 v1, v5, v199
	v_mul_f32_e32 v2, v4, v200
	v_mul_f32_e32 v4, v59, v24
	v_mul_f32_e32 v3, v4, v201
	v_cvt_pk_bf16_f32 v0, v0, v1
	v_cvt_pk_bf16_f32 v1, v2, v3
	ds_write_b64 v25, v[0:1] offset:32
	v_mul_f32_e32 v4, v60, v24
	v_mul_f32_e32 v5, v61, v24
	s_waitcnt vmcnt(0) lgkmcnt(0)
	v_mul_f32_e32 v0, v4, v202
	v_mul_f32_e32 v1, v5, v203
	v_mul_f32_e32 v2, v6, v204
	v_mul_f32_e32 v3, v7, v205
	v_cvt_pk_bf16_f32 v0, v0, v1
	v_cvt_pk_bf16_f32 v1, v2, v3
	ds_write_b64 v25, v[0:1] offset:48
	v_mul_f32_e32 v4, v75, v24
	v_mul_f32_e32 v5, v76, v24
	v_mul_f32_e32 v6, v77, v24
	v_mul_f32_e32 v7, v78, v24
	s_waitcnt vmcnt(0) lgkmcnt(0)
	v_mul_f32_e32 v0, v4, v206
	v_mul_f32_e32 v1, v5, v207
	v_mul_f32_e32 v2, v6, v208
	v_mul_f32_e32 v3, v7, v209
	v_cvt_pk_bf16_f32 v0, v0, v1
	v_cvt_pk_bf16_f32 v1, v2, v3
	ds_write_b64 v25, v[0:1] offset:64
	v_mul_f32_e32 v4, v79, v24
	v_mul_f32_e32 v5, v80, v24
	v_mul_f32_e32 v6, v81, v24
	v_mul_f32_e32 v7, v82, v24
	s_waitcnt vmcnt(0) lgkmcnt(0)
	v_mul_f32_e32 v0, v4, v210
	v_mul_f32_e32 v1, v5, v211
	v_mul_f32_e32 v2, v6, v212
	v_mul_f32_e32 v3, v7, v213
	v_cvt_pk_bf16_f32 v0, v0, v1
	v_cvt_pk_bf16_f32 v1, v2, v3
	ds_write_b64 v25, v[0:1] offset:80
	v_mul_f32_e32 v4, v83, v24
	v_mul_f32_e32 v5, v84, v24
	v_mul_f32_e32 v6, v85, v24
	v_mul_f32_e32 v7, v86, v24
	s_waitcnt vmcnt(0) lgkmcnt(0)
	v_mul_f32_e32 v0, v4, v214
	v_mul_f32_e32 v1, v5, v215
	v_mul_f32_e32 v2, v6, v216
	v_mul_f32_e32 v3, v7, v217
	v_cvt_pk_bf16_f32 v0, v0, v1
	v_cvt_pk_bf16_f32 v1, v2, v3
	ds_write_b64 v25, v[0:1] offset:96
	v_mul_f32_e32 v4, v87, v24
	v_mul_f32_e32 v5, v88, v24
	v_mul_f32_e32 v6, v89, v24
	v_mul_f32_e32 v7, v90, v24
	s_waitcnt vmcnt(0) lgkmcnt(0)
	v_mul_f32_e32 v0, v4, v218
	v_mul_f32_e32 v1, v5, v219
	v_mul_f32_e32 v2, v6, v220
	v_mul_f32_e32 v3, v7, v221
	v_cvt_pk_bf16_f32 v0, v0, v1
	v_cvt_pk_bf16_f32 v1, v2, v3
	ds_write_b64 v25, v[0:1] offset:112
	v_mul_f32_e32 v4, v91, v24
	v_mul_f32_e32 v5, v92, v24
	v_mul_f32_e32 v6, v93, v24
	v_mul_f32_e32 v7, v94, v24
	s_waitcnt vmcnt(0) lgkmcnt(0)
	v_mul_f32_e32 v0, v4, v222
	v_mul_f32_e32 v1, v5, v223
	v_mul_f32_e32 v2, v6, v224
	v_mul_f32_e32 v3, v7, v225
	v_cvt_pk_bf16_f32 v0, v0, v1
	v_cvt_pk_bf16_f32 v1, v2, v3
	ds_write_b64 v25, v[0:1] offset:128
	v_mul_f32_e32 v4, v95, v24
	v_mul_f32_e32 v5, v96, v24
	v_mul_f32_e32 v6, v97, v24
	v_mul_f32_e32 v7, v98, v24
	s_waitcnt vmcnt(0) lgkmcnt(0)
	v_mul_f32_e32 v0, v4, v232
	v_mul_f32_e32 v1, v5, v233
	v_mul_f32_e32 v2, v6, v234
	v_mul_f32_e32 v3, v7, v235
	v_cvt_pk_bf16_f32 v0, v0, v1
	v_cvt_pk_bf16_f32 v1, v2, v3
	ds_write_b64 v25, v[0:1] offset:144
	v_mul_f32_e32 v4, v99, v24
	v_mul_f32_e32 v5, v100, v24
	v_mul_f32_e32 v6, v101, v24
	v_mul_f32_e32 v7, v56, v24
	s_waitcnt vmcnt(0) lgkmcnt(0)
; DEV void epi_ukv(f32x16 (&acc)[1][8], const Params& P, int layer, int batch, int m0, int head, int wid, int r32, int hi, char* lds) {
;     ...
; #pragma unroll
;   for (int ni = 0; ni < 4; ++ni)
; #pragma unroll
;     for (int r4 = 0; r4 < 4; ++r4) {
;       const int c = ni * 32 + r4 * 8 + hi * 4;
;       const float4 gg = *reinterpret_cast<const float4*>(g + c);
;       const f32x16& a = acc[0][ni];
;       st4lds(dst, c, a[r4 * 4] * inv * gg.x, a[r4 * 4 + 1] * inv * gg.y, a[r4 * 4 + 2] * inv * gg.z, a[r4 * 4 + 3] * inv * gg.w);
;     }
;   const int pos = batch ? t : (t & 4095);
;   const float2* rp = WS{P.ws}.rope() + (long)pos * 32;
; #pragma unroll
;   for (int r4 = 0; r4 < 4; ++r4) {
;     const int i = r4 * 8 + hi * 4;
;     const float4 g1 = *reinterpret_cast<const float4*>(g + 128 + i), g2 = *reinterpret_cast<const float4*>(g + 160 + i);
;     const float4 cs01 = *reinterpret_cast<const float4*>(rp + i), cs23 = *reinterpret_cast<const float4*>(rp + i + 2);
;     const float x1[4] = {kr[0][r4].x * inv * g1.x, kr[0][r4].y * inv * g1.y, kr[0][r4].z * inv * g1.z, kr[0][r4].w * inv * g1.w};
;     const float x2[4] = {kr[1][r4].x * inv * g2.x, kr[1][r4].y * inv * g2.y, kr[1][r4].z * inv * g2.z, kr[1][r4].w * inv * g2.w};
;     const float cc[4] = {cs01.x, cs01.z, cs23.x, cs23.z}, sn[4] = {cs01.y, cs01.w, cs23.y, cs23.w};
;     st4lds(dst, 128 + i, x1[0] * cc[0] - x2[0] * sn[0], x1[1] * cc[1] - x2[1] * sn[1], x1[2] * cc[2] - x2[2] * sn[2], x1[3] * cc[3] - x2[3] * sn[3]);
;     st4lds(dst, 160 + i, x1[0] * sn[0] + x2[0] * cc[0], x1[1] * sn[1] + x2[1] * cc[1], x1[2] * sn[2] + x2[2] * cc[2], x1[3] * sn[3] + x2[3] * cc[3]);
	v_mul_f32_e32 v0, v4, v236
	v_mul_f32_e32 v1, v5, v237
	v_mul_f32_e32 v2, v6, v238
	v_mul_f32_e32 v3, v7, v239
	v_cvt_pk_bf16_f32 v0, v0, v1
	v_cvt_pk_bf16_f32 v1, v2, v3
	ds_write_b64 v25, v[0:1] offset:160
	v_mul_f32_e32 v4, v28, v24
	v_mul_f32_e32 v5, v29, v24
	v_mul_f32_e32 v6, v30, v24
	v_mul_f32_e32 v7, v31, v24
	v_mov_b32_e32 v30, v48
	v_mov_b32_e32 v31, v52
	v_mov_b32_e32 v52, v49
	v_mov_b32_e32 v48, v50
	v_mov_b32_e32 v49, v54
	v_mov_b32_e32 v54, v51
	v_pk_mul_f32 v[30:31], v[30:31], v[24:25] op_sel_hi:[1,0]
	v_pk_mul_f32 v[50:51], v[52:53], v[24:25] op_sel_hi:[1,0]
	v_pk_mul_f32 v[48:49], v[48:49], v[24:25] op_sel_hi:[1,0]
	v_pk_mul_f32 v[52:53], v[54:55], v[24:25] op_sel_hi:[1,0]
	s_waitcnt vmcnt(0) lgkmcnt(0)
	v_mul_f32_e32 v0, v4, v240
	v_mul_f32_e32 v1, v5, v241
	v_mul_f32_e32 v2, v6, v242
	v_mul_f32_e32 v3, v7, v243
	v_cvt_pk_bf16_f32 v0, v0, v1
	v_cvt_pk_bf16_f32 v1, v2, v3
	ds_write_b64 v25, v[0:1] offset:176
	v_mul_f32_e32 v4, v57, v24
	v_mul_f32_e32 v5, v102, v24
	v_mul_f32_e32 v6, v103, v24
	v_mul_f32_e32 v7, v104, v24
	s_waitcnt vmcnt(0) lgkmcnt(0)
	v_mul_f32_e32 v0, v4, v244
	v_mul_f32_e32 v1, v5, v245
	v_mul_f32_e32 v2, v6, v246
	v_mul_f32_e32 v3, v7, v247
	v_cvt_pk_bf16_f32 v0, v0, v1
	v_cvt_pk_bf16_f32 v1, v2, v3
	ds_write_b64 v25, v[0:1] offset:192
	v_mul_f32_e32 v4, v105, v24
	v_mul_f32_e32 v5, v106, v24
	v_mul_f32_e32 v6, v107, v24
	v_mul_f32_e32 v7, v108, v24
	s_waitcnt vmcnt(0) lgkmcnt(0)
	v_mul_f32_e32 v0, v4, v248
	v_mul_f32_e32 v1, v5, v249
	v_mul_f32_e32 v2, v6, v250
	v_mul_f32_e32 v3, v7, v251
	v_cvt_pk_bf16_f32 v0, v0, v1
	v_cvt_pk_bf16_f32 v1, v2, v3
	ds_write_b64 v25, v[0:1] offset:208
	v_mul_f32_e32 v4, v8, v24
	v_mul_f32_e32 v5, v9, v24
	v_mul_f32_e32 v6, v10, v24
	v_mul_f32_e32 v7, v11, v24
	v_bitop3_b32 v8, v148, s2, v154 bitop3:0xc8
	v_cndmask_b32_e64 v8, v150, v8, s[26:27]
	v_ashrrev_i32_e32 v9, 31, v8
	v_lshlrev_b64 v[8:9], 8, v[8:9]
	v_lshl_add_u64 v[8:9], s[12:13], 0, v[8:9]
	v_lshl_add_u64 v[28:29], v[8:9], 0, v[184:185]
	s_waitcnt vmcnt(0) lgkmcnt(0)
	v_mul_f32_e32 v0, v4, v170
	v_mul_f32_e32 v1, v5, v171
	v_mul_f32_e32 v2, v6, v172
	v_mul_f32_e32 v3, v7, v173
	v_cvt_pk_bf16_f32 v0, v0, v1
	v_cvt_pk_bf16_f32 v1, v2, v3
	ds_write_b64 v25, v[0:1] offset:224
	v_mul_f32_e32 v4, v12, v24
	v_mul_f32_e32 v5, v13, v24
	v_mul_f32_e32 v6, v14, v24
	v_mul_f32_e32 v7, v15, v24
	s_waitcnt vmcnt(0) lgkmcnt(0)
	v_mul_f32_e32 v0, v4, v174
	v_mul_f32_e32 v1, v5, v175
	v_mul_f32_e32 v2, v6, v176
	v_mul_f32_e32 v3, v7, v177
	v_cvt_pk_bf16_f32 v0, v0, v1
	v_cvt_pk_bf16_f32 v1, v2, v3
	ds_write_b64 v25, v[0:1] offset:240
	flat_load_dwordx4 v[0:3], v[26:27] offset:2560
	flat_load_dwordx4 v[4:7], v[26:27] offset:2688
	flat_load_dwordx4 v[8:11], v[28:29]
	flat_load_dwordx4 v[12:15], v[28:29] offset:16
	s_waitcnt vmcnt(0) lgkmcnt(0)
	v_mov_b32_e32 v54, v0
	v_mov_b32_e32 v55, v4
	v_mov_b32_e32 v4, v1
	v_mov_b32_e32 v0, v2
	v_mov_b32_e32 v1, v6
	v_mov_b32_e32 v6, v3
	v_pk_mul_f32 v[2:3], v[30:31], v[54:55]
	v_pk_mul_f32 v[4:5], v[50:51], v[4:5]
	v_pk_mul_f32 v[0:1], v[48:49], v[0:1]
	v_pk_mul_f32 v[6:7], v[52:53], v[6:7]
	v_pk_mul_f32 v[30:31], v[2:3], v[8:9]
	v_pk_mul_f32 v[48:49], v[4:5], v[10:11]
	v_pk_mul_f32 v[50:51], v[0:1], v[12:13]
	v_pk_mul_f32 v[52:53], v[6:7], v[14:15]
	v_pk_mul_f32 v[2:3], v[2:3], v[8:9] op_sel:[1,0] op_sel_hi:[0,1]
	v_pk_mul_f32 v[4:5], v[4:5], v[10:11] op_sel:[1,0] op_sel_hi:[0,1]
	v_pk_mul_f32 v[0:1], v[0:1], v[12:13] op_sel:[1,0] op_sel_hi:[0,1]
	v_pk_mul_f32 v[6:7], v[6:7], v[14:15] op_sel:[1,0] op_sel_hi:[0,1]
	v_sub_f32_e32 v8, v30, v31
	v_sub_f32_e32 v9, v48, v49
	v_sub_f32_e32 v10, v50, v51
	v_sub_f32_e32 v11, v52, v53
	v_add_f32_e32 v2, v2, v3
	v_add_f32_e32 v3, v4, v5
	v_add_f32_e32 v4, v0, v1
	v_cvt_pk_bf16_f32 v0, v8, v9
	v_cvt_pk_bf16_f32 v1, v10, v11
	v_add_f32_e32 v5, v6, v7
	ds_write_b64 v25, v[0:1] offset:256
	v_cvt_pk_bf16_f32 v0, v2, v3
	v_cvt_pk_bf16_f32 v1, v4, v5
	ds_write_b64 v25, v[0:1] offset:320
	flat_load_dwordx4 v[0:3], v[26:27] offset:2592
	flat_load_dwordx4 v[4:7], v[26:27] offset:2720
	flat_load_dwordx4 v[8:11], v[28:29] offset:64
	flat_load_dwordx4 v[12:15], v[28:29] offset:80
	v_mov_b32_e32 v30, v40
	v_mov_b32_e32 v31, v44
	v_mov_b32_e32 v44, v41
	v_mov_b32_e32 v40, v42
	v_mov_b32_e32 v41, v46
	v_mov_b32_e32 v46, v43
	v_pk_mul_f32 v[30:31], v[30:31], v[24:25] op_sel_hi:[1,0]
	v_pk_mul_f32 v[42:43], v[44:45], v[24:25] op_sel_hi:[1,0]
	v_pk_mul_f32 v[40:41], v[40:41], v[24:25] op_sel_hi:[1,0]
	v_pk_mul_f32 v[44:45], v[46:47], v[24:25] op_sel_hi:[1,0]
	s_waitcnt vmcnt(0) lgkmcnt(0)
; #define LDSP(T) __attribute__((address_space(3))) T*
; template <int NCH, int STRIDE> DEV void slab_flush(char* slab, u16* grow0, int gstride, int lane) {
;   asm volatile("s_waitcnt lgkmcnt(0)" ::: "memory");
; #pragma unroll
;   for (int i = 0; i < NCH / 2; ++i) {
;     const int q = i * 64 + lane, row = q / NCH, cc = q - row * NCH;
;     const u32x4 v = *(LDSP(const u32x4))(slab + row * STRIDE + cc * 16);
;     *reinterpret_cast<u32x4*>(grow0 + (long)row * gstride + cc * 8) = v;
;   }
; DEV void epi_ukv(f32x16 (&acc)[1][8], const Params& P, int layer, int batch, int m0, int head, int wid, int r32, int hi, char* lds) {
;     ...
; #pragma unroll
;   for (int r4 = 0; r4 < 4; ++r4) {
;     const int i = r4 * 8 + hi * 4;
;     const float4 g1 = *reinterpret_cast<const float4*>(g + 128 + i), g2 = *reinterpret_cast<const float4*>(g + 160 + i);
;     const float4 cs01 = *reinterpret_cast<const float4*>(rp + i), cs23 = *reinterpret_cast<const float4*>(rp + i + 2);
;     const float x1[4] = {kr[0][r4].x * inv * g1.x, kr[0][r4].y * inv * g1.y, kr[0][r4].z * inv * g1.z, kr[0][r4].w * inv * g1.w};
;     const float x2[4] = {kr[1][r4].x * inv * g2.x, kr[1][r4].y * inv * g2.y, kr[1][r4].z * inv * g2.z, kr[1][r4].w * inv * g2.w};
;     const float cc[4] = {cs01.x, cs01.z, cs23.x, cs23.z}, sn[4] = {cs01.y, cs01.w, cs23.y, cs23.w};
;     st4lds(dst, 128 + i, x1[0] * cc[0] - x2[0] * sn[0], x1[1] * cc[1] - x2[1] * sn[1], x1[2] * cc[2] - x2[2] * sn[2], x1[3] * cc[3] - x2[3] * sn[3]);
;     st4lds(dst, 160 + i, x1[0] * sn[0] + x2[0] * cc[0], x1[1] * sn[1] + x2[1] * cc[1], x1[2] * sn[2] + x2[2] * cc[2], x1[3] * sn[3] + x2[3] * cc[3]);
;   }
;   slab_flush<24, 400>(slab, WS{P.ws}.KB() + (long)(m0 + wid * 32) * 768 + head * 192, 768, hi * 32 + r32);
	v_mov_b32_e32 v46, v0
	v_mov_b32_e32 v47, v4
	v_mov_b32_e32 v4, v1
	v_mov_b32_e32 v0, v2
	v_mov_b32_e32 v1, v6
	v_mov_b32_e32 v6, v3
	v_pk_mul_f32 v[2:3], v[30:31], v[46:47]
	v_pk_mul_f32 v[4:5], v[42:43], v[4:5]
	v_pk_mul_f32 v[0:1], v[40:41], v[0:1]
	v_pk_mul_f32 v[6:7], v[44:45], v[6:7]
	v_pk_mul_f32 v[30:31], v[2:3], v[8:9]
	v_pk_mul_f32 v[40:41], v[4:5], v[10:11]
	v_pk_mul_f32 v[42:43], v[0:1], v[12:13]
	v_pk_mul_f32 v[44:45], v[6:7], v[14:15]
	v_pk_mul_f32 v[2:3], v[2:3], v[8:9] op_sel:[1,0] op_sel_hi:[0,1]
	v_pk_mul_f32 v[4:5], v[4:5], v[10:11] op_sel:[1,0] op_sel_hi:[0,1]
	v_pk_mul_f32 v[0:1], v[0:1], v[12:13] op_sel:[1,0] op_sel_hi:[0,1]
	v_pk_mul_f32 v[6:7], v[6:7], v[14:15] op_sel:[1,0] op_sel_hi:[0,1]
	v_sub_f32_e32 v8, v30, v31
	v_sub_f32_e32 v9, v40, v41
	v_sub_f32_e32 v10, v42, v43
	v_sub_f32_e32 v11, v44, v45
	v_add_f32_e32 v2, v2, v3
	v_add_f32_e32 v3, v4, v5
	v_add_f32_e32 v4, v0, v1
	v_cvt_pk_bf16_f32 v0, v8, v9
	v_cvt_pk_bf16_f32 v1, v10, v11
	v_add_f32_e32 v5, v6, v7
	ds_write_b64 v25, v[0:1] offset:272
	v_cvt_pk_bf16_f32 v0, v2, v3
	v_cvt_pk_bf16_f32 v1, v4, v5
	ds_write_b64 v25, v[0:1] offset:336
	flat_load_dwordx4 v[8:11], v[26:27] offset:2624
	flat_load_dwordx4 v[4:7], v[26:27] offset:2752
	flat_load_dwordx4 v[0:3], v[28:29] offset:128
	flat_load_dwordx4 v[12:15], v[28:29] offset:144
	v_and_b32_e32 v40, 63, v152
	v_mul_lo_u16_e32 v41, 43, v40
	v_or_b32_e32 v42, 64, v40
	v_or_b32_e32 v43, 0x80, v40
	v_lshrrev_b16_e32 v41, 10, v41
	v_mul_lo_u16_e32 v53, 43, v42
	v_mul_lo_u16_e32 v54, 0xab, v43
	v_or_b32_e32 v44, 0xc0, v40
	v_or_b32_e32 v45, 0x100, v40
	v_or_b32_e32 v46, 0x180, v40
	v_or_b32_e32 v47, 0x140, v40
	v_or_b32_e32 v48, 0x200, v40
	v_or_b32_e32 v49, 0x1c0, v40
	v_or_b32_e32 v50, 0x280, v40
	v_or_b32_e32 v51, 0x240, v40
	v_or_b32_e32 v52, 0x2c0, v40
	v_mad_i32_i24 v40, v41, s58, v40
	v_mul_u32_u24_e32 v64, 0x190, v41
	v_mul_u32_u24_e32 v65, 0x300, v41
	v_lshrrev_b16_e32 v41, 10, v53
	v_lshrrev_b16_e32 v53, 12, v54
	v_mad_i32_i24 v69, v41, s58, v42
	v_mad_i32_i24 v72, v53, s58, v43
	v_mov_b32_e32 v42, v36
	v_mov_b32_e32 v43, v20
	v_mov_b32_e32 v20, v37
	v_mov_b32_e32 v36, v38
	v_mov_b32_e32 v37, v22
	v_mov_b32_e32 v22, v39
	v_pk_mul_f32 v[38:39], v[42:43], v[24:25] op_sel_hi:[1,0]
	v_pk_mul_f32 v[20:21], v[20:21], v[24:25] op_sel_hi:[1,0]
	v_pk_mul_f32 v[36:37], v[36:37], v[24:25] op_sel_hi:[1,0]
	v_pk_mul_f32 v[22:23], v[22:23], v[24:25] op_sel_hi:[1,0]
	v_mul_lo_u16_e32 v55, 0xab, v44
	v_mul_u32_u24_e32 v56, 0xaab, v45
	v_mul_u32_u24_e32 v57, 0xaab, v47
	v_mul_u32_u24_e32 v58, 0xaab, v46
	v_mul_u32_u24_e32 v59, 0xaab, v49
	v_mul_u32_u24_e32 v60, 0xaab, v48
	v_mul_u32_u24_e32 v61, 0xaab, v51
	v_mul_u32_u24_e32 v62, 0xaab, v50
	v_mov_b64_e32 v[30:31], s[70:71]
	v_mul_u32_u24_e32 v63, 0xaab, v52
	v_lshrrev_b16_e32 v54, 12, v55
	v_lshrrev_b32_e32 v55, 16, v56
	v_lshrrev_b32_e32 v56, 16, v57
	v_lshrrev_b32_e32 v66, 16, v58
	v_perm_b32 v57, v58, v57, s44
	v_lshrrev_b32_e32 v58, 16, v59
	v_lshrrev_b32_e32 v67, 16, v60
	v_perm_b32 v59, v60, v59, s44
	v_lshrrev_b32_e32 v60, 16, v61
	v_lshrrev_b32_e32 v68, 16, v62
	v_mad_i64_i32 v[30:31], s[2:3], v148, s39, v[30:31]
	v_perm_b32 v61, v62, v61, s44
	v_lshrrev_b32_e32 v62, 16, v63
	v_lshlrev_b32_e32 v63, 4, v40
	v_mad_i32_i24 v48, v67, s58, v48
	v_mad_i32_i24 v51, v60, s58, v51
	v_mad_i32_i24 v50, v68, s58, v50
	v_mad_i32_i24 v52, v62, s58, v52
	v_lshlrev_b32_e32 v75, 4, v48
	v_lshlrev_b32_e32 v77, 4, v51
	v_lshlrev_b32_e32 v78, 4, v50
	v_lshlrev_b32_e32 v40, 3, v40
	v_lshlrev_b32_e32 v184, 1, v65
	v_mul_u32_u24_e32 v70, 0x190, v41
	v_mul_u32_u24_e32 v71, 0x300, v41
	v_ashrrev_i32_e32 v41, 31, v40
	v_lshlrev_b32_e32 v79, 4, v52
	s_waitcnt vmcnt(0) lgkmcnt(0)
	v_mov_b32_e32 v42, v8
	v_mov_b32_e32 v43, v4
	v_mov_b32_e32 v4, v9
	v_mov_b32_e32 v8, v10
	v_mov_b32_e32 v9, v6
	v_mov_b32_e32 v6, v11
	v_pk_mul_f32 v[10:11], v[38:39], v[42:43]
	v_pk_mul_f32 v[4:5], v[20:21], v[4:5]
	v_pk_mul_f32 v[8:9], v[36:37], v[8:9]
	v_pk_mul_f32 v[6:7], v[22:23], v[6:7]
	v_pk_mul_f32 v[20:21], v[10:11], v[0:1]
	v_pk_mul_f32 v[22:23], v[4:5], v[2:3]
	v_pk_mul_f32 v[36:37], v[8:9], v[12:13]
	v_pk_mul_f32 v[38:39], v[6:7], v[14:15]
	v_pk_mul_f32 v[0:1], v[10:11], v[0:1] op_sel:[1,0] op_sel_hi:[0,1]
	v_pk_mul_f32 v[2:3], v[4:5], v[2:3] op_sel:[1,0] op_sel_hi:[0,1]
	v_pk_mul_f32 v[4:5], v[8:9], v[12:13] op_sel:[1,0] op_sel_hi:[0,1]
	v_pk_mul_f32 v[6:7], v[6:7], v[14:15] op_sel:[1,0] op_sel_hi:[0,1]
	v_sub_f32_e32 v8, v20, v21
	v_sub_f32_e32 v9, v22, v23
	v_sub_f32_e32 v10, v36, v37
	v_sub_f32_e32 v11, v38, v39
	v_add_f32_e32 v12, v0, v1
	v_cvt_pk_bf16_f32 v0, v8, v9
	v_cvt_pk_bf16_f32 v1, v10, v11
	v_add_f32_e32 v2, v2, v3
	v_add_f32_e32 v3, v4, v5
	v_add_f32_e32 v4, v6, v7
	ds_write_b64 v25, v[0:1] offset:288
	v_cvt_pk_bf16_f32 v0, v12, v2
	v_cvt_pk_bf16_f32 v1, v3, v4
	ds_write_b64 v25, v[0:1] offset:352
	flat_load_dwordx4 v[0:3], v[26:27] offset:2656
	flat_load_dwordx4 v[4:7], v[26:27] offset:2784
	flat_load_dwordx4 v[8:11], v[28:29] offset:192
	flat_load_dwordx4 v[12:15], v[28:29] offset:208
	v_mad_i32_i24 v23, v54, s58, v44
	v_mad_i32_i24 v36, v55, s58, v45
	v_mad_i32_i24 v38, v56, s58, v47
	v_mad_i32_i24 v42, v66, s58, v46
	v_mad_i32_i24 v44, v58, s58, v49
	v_pk_mul_lo_u16 v46, v59, s37 op_sel_hi:[1,0]
	v_mul_u32_u24_e32 v39, 0x190, v55
	v_mul_u32_u24_e32 v45, 0x300, v55
	v_pk_mul_lo_u16 v29, v57, s37 op_sel_hi:[1,0]
	v_mul_u32_u24_e32 v47, 0x300, v56
	v_mul_u32_u24_e32 v55, 0x300, v67
	v_pk_mul_lo_u16 v56, v61, s37 op_sel_hi:[1,0]
	v_mul_u32_u24_e32 v57, 0x300, v60
	v_mul_u32_u24_e32 v59, 0x190, v62
	v_mul_u32_u24_e32 v60, 0x300, v62
	v_lshl_add_u64 v[20:21], v[30:31], 0, s[22:23]
; #define LDSP(T) __attribute__((address_space(3))) T*
; template <int NCH, int STRIDE> DEV void slab_flush(char* slab, u16* grow0, int gstride, int lane) {
;   asm volatile("s_waitcnt lgkmcnt(0)" ::: "memory");
; #pragma unroll
;   for (int i = 0; i < NCH / 2; ++i) {
;     const int q = i * 64 + lane, row = q / NCH, cc = q - row * NCH;
;     const u32x4 v = *(LDSP(const u32x4))(slab + row * STRIDE + cc * 16);
;     *reinterpret_cast<u32x4*>(grow0 + (long)row * gstride + cc * 8) = v;
;   }
;   asm volatile("s_waitcnt lgkmcnt(0)" ::: "memory");
; }
; DEV void epi_ukv(f32x16 (&acc)[1][8], const Params& P, int layer, int batch, int m0, int head, int wid, int r32, int hi, char* lds) {
;     ...
;   for (int r4 = 0; r4 < 4; ++r4) {
;     const int i = r4 * 8 + hi * 4;
;     const float4 g1 = *reinterpret_cast<const float4*>(g + 128 + i), g2 = *reinterpret_cast<const float4*>(g + 160 + i);
;     const float4 cs01 = *reinterpret_cast<const float4*>(rp + i), cs23 = *reinterpret_cast<const float4*>(rp + i + 2);
;     const float x1[4] = {kr[0][r4].x * inv * g1.x, kr[0][r4].y * inv * g1.y, kr[0][r4].z * inv * g1.z, kr[0][r4].w * inv * g1.w};
;     const float x2[4] = {kr[1][r4].x * inv * g2.x, kr[1][r4].y * inv * g2.y, kr[1][r4].z * inv * g2.z, kr[1][r4].w * inv * g2.w};
;     const float cc[4] = {cs01.x, cs01.z, cs23.x, cs23.z}, sn[4] = {cs01.y, cs01.w, cs23.y, cs23.w};
;     st4lds(dst, 128 + i, x1[0] * cc[0] - x2[0] * sn[0], x1[1] * cc[1] - x2[1] * sn[1], x1[2] * cc[2] - x2[2] * sn[2], x1[3] * cc[3] - x2[3] * sn[3]);
;     st4lds(dst, 160 + i, x1[0] * sn[0] + x2[0] * cc[0], x1[1] * sn[1] + x2[1] * cc[1], x1[2] * sn[2] + x2[2] * cc[2], x1[3] * sn[3] + x2[3] * cc[3]);
;   }
;   slab_flush<24, 400>(slab, WS{P.ws}.KB() + (long)(m0 + wid * 32) * 768 + head * 192, 768, hi * 32 + r32);
	v_add3_u32 v61, v153, v64, v63
	v_lshlrev_b32_e32 v31, 4, v69
	v_lshlrev_b32_e32 v22, 3, v69
	v_lshlrev_b32_e32 v62, 4, v72
	v_lshlrev_b32_e32 v26, 3, v72
	v_lshlrev_b32_e32 v64, 4, v36
	v_lshlrev_b32_e32 v30, 3, v36
	v_lshlrev_b32_e32 v67, 4, v38
	v_lshlrev_b32_e32 v36, 3, v38
	v_lshlrev_b32_e32 v69, 4, v42
	v_lshlrev_b32_e32 v38, 3, v42
	v_and_b32_e32 v72, 0xfff0, v46
	v_lshlrev_b32_e32 v73, 4, v44
	v_lshlrev_b32_e32 v42, 3, v44
	v_lshrrev_b32_e32 v74, 16, v46
	v_lshlrev_b32_e32 v44, 3, v48
	v_lshlrev_b32_e32 v46, 3, v51
	v_lshlrev_b32_e32 v48, 3, v50
	v_mov_b32_e32 v50, v32
	v_mov_b32_e32 v51, v16
	v_mov_b32_e32 v16, v33
	v_mov_b32_e32 v32, v34
	v_mov_b32_e32 v33, v18
	v_mov_b32_e32 v18, v35
	v_pk_mul_f32 v[34:35], v[50:51], v[24:25] op_sel_hi:[1,0]
	v_pk_mul_f32 v[16:17], v[16:17], v[24:25] op_sel_hi:[1,0]
	v_pk_mul_f32 v[32:33], v[32:33], v[24:25] op_sel_hi:[1,0]
	v_pk_mul_f32 v[18:19], v[18:19], v[24:25] op_sel_hi:[1,0]
	v_add3_u32 v70, v153, v70, v31
	v_lshlrev_b32_e32 v63, 4, v23
	v_lshlrev_b32_e32 v28, 3, v23
	v_ashrrev_i32_e32 v23, 31, v22
	v_mul_u32_u24_e32 v27, 0x190, v53
	v_add3_u32 v62, v153, v27, v62
	v_mul_u32_u24_e32 v43, 0x300, v53
	v_ashrrev_i32_e32 v27, 31, v26
	v_mul_u32_u24_e32 v37, 0x190, v54
	v_add3_u32 v63, v153, v37, v63
	v_mul_u32_u24_e32 v53, 0x300, v54
	v_mul_u32_u24_e32 v54, 0x300, v66
	v_mul_u32_u24_e32 v49, 0x300, v58
	v_mul_u32_u24_e32 v58, 0x300, v68
	v_and_b32_e32 v66, 0xfff0, v29
	v_lshrrev_b32_e32 v68, 16, v29
	v_ashrrev_i32_e32 v29, 31, v28
	v_add3_u32 v64, v153, v39, v64
	v_ashrrev_i32_e32 v31, 31, v30
	v_add3_u32 v66, v153, v66, v67
	v_ashrrev_i32_e32 v37, 31, v36
	v_ashrrev_i32_e32 v39, 31, v38
	v_and_b32_e32 v76, 0xfff0, v56
	v_lshrrev_b32_e32 v56, 16, v56
	s_waitcnt vmcnt(0) lgkmcnt(0)
	v_mov_b32_e32 v50, v0
	v_mov_b32_e32 v51, v4
	v_mov_b32_e32 v4, v1
	v_mov_b32_e32 v0, v2
	v_mov_b32_e32 v1, v6
	v_mov_b32_e32 v6, v3
	v_pk_mul_f32 v[2:3], v[34:35], v[50:51]
	v_pk_mul_f32 v[4:5], v[16:17], v[4:5]
	v_pk_mul_f32 v[0:1], v[32:33], v[0:1]
	v_pk_mul_f32 v[6:7], v[18:19], v[6:7]
	v_pk_mul_f32 v[16:17], v[2:3], v[8:9]
	v_pk_mul_f32 v[18:19], v[4:5], v[10:11]
	v_pk_mul_f32 v[32:33], v[0:1], v[12:13]
	v_pk_mul_f32 v[34:35], v[6:7], v[14:15]
	v_pk_mul_f32 v[2:3], v[2:3], v[8:9] op_sel:[1,0] op_sel_hi:[0,1]
	v_pk_mul_f32 v[4:5], v[4:5], v[10:11] op_sel:[1,0] op_sel_hi:[0,1]
	v_pk_mul_f32 v[0:1], v[0:1], v[12:13] op_sel:[1,0] op_sel_hi:[0,1]
	v_pk_mul_f32 v[6:7], v[6:7], v[14:15] op_sel:[1,0] op_sel_hi:[0,1]
	v_sub_f32_e32 v8, v16, v17
	v_sub_f32_e32 v9, v18, v19
	v_sub_f32_e32 v10, v32, v33
	v_sub_f32_e32 v11, v34, v35
	v_add_f32_e32 v2, v2, v3
	v_add_f32_e32 v3, v4, v5
	v_add_f32_e32 v4, v0, v1
	v_cvt_pk_bf16_f32 v0, v8, v9
	v_cvt_pk_bf16_f32 v1, v10, v11
	v_add_f32_e32 v5, v6, v7
	ds_write_b64 v25, v[0:1] offset:304
	v_cvt_pk_bf16_f32 v0, v2, v3
	v_cvt_pk_bf16_f32 v1, v4, v5
	ds_write_b64 v25, v[0:1] offset:368
	s_waitcnt lgkmcnt(0)
	ds_read_b128 v[0:3], v61
	v_lshl_add_u64 v[4:5], v[20:21], 0, v[184:185]
	v_lshl_add_u64 v[4:5], v[40:41], 1, v[4:5]
	v_lshlrev_b32_e32 v184, 1, v71
	v_add3_u32 v6, v153, v68, v69
	s_waitcnt lgkmcnt(0)
	flat_store_dwordx4 v[4:5], v[0:3]
	ds_read_b128 v[0:3], v70
	v_lshl_add_u64 v[4:5], v[20:21], 0, v[184:185]
	v_lshl_add_u64 v[4:5], v[22:23], 1, v[4:5]
	v_lshlrev_b32_e32 v184, 1, v43
	v_add3_u32 v7, v153, v72, v73
	s_waitcnt lgkmcnt(0)
	flat_store_dwordx4 v[4:5], v[0:3]
	ds_read_b128 v[0:3], v62
	v_lshl_add_u64 v[4:5], v[20:21], 0, v[184:185]
	v_lshl_add_u64 v[4:5], v[26:27], 1, v[4:5]
	v_lshlrev_b32_e32 v184, 1, v53
	v_ashrrev_i32_e32 v43, 31, v42
	s_waitcnt lgkmcnt(0)
	flat_store_dwordx4 v[4:5], v[0:3]
	ds_read_b128 v[0:3], v63
	v_lshl_add_u64 v[4:5], v[20:21], 0, v[184:185]
	v_lshl_add_u64 v[4:5], v[28:29], 1, v[4:5]
	v_lshlrev_b32_e32 v184, 1, v45
	v_add3_u32 v8, v153, v74, v75
	s_waitcnt lgkmcnt(0)
	flat_store_dwordx4 v[4:5], v[0:3]
	ds_read_b128 v[0:3], v64
	v_lshl_add_u64 v[4:5], v[20:21], 0, v[184:185]
	v_lshl_add_u64 v[4:5], v[30:31], 1, v[4:5]
	v_lshlrev_b32_e32 v184, 1, v47
	v_ashrrev_i32_e32 v45, 31, v44
	s_waitcnt lgkmcnt(0)
	flat_store_dwordx4 v[4:5], v[0:3]
	ds_read_b128 v[0:3], v66
	v_lshl_add_u64 v[4:5], v[20:21], 0, v[184:185]
	v_lshl_add_u64 v[4:5], v[36:37], 1, v[4:5]
	v_lshlrev_b32_e32 v184, 1, v54
	v_ashrrev_i32_e32 v47, 31, v46
	s_waitcnt lgkmcnt(0)
	flat_store_dwordx4 v[4:5], v[0:3]
	ds_read_b128 v[0:3], v6
	v_lshl_add_u64 v[4:5], v[20:21], 0, v[184:185]
	v_lshl_add_u64 v[4:5], v[38:39], 1, v[4:5]
	v_lshlrev_b32_e32 v184, 1, v49
	v_add3_u32 v6, v153, v76, v77
	s_waitcnt lgkmcnt(0)
	flat_store_dwordx4 v[4:5], v[0:3]
	ds_read_b128 v[0:3], v7
	v_lshl_add_u64 v[4:5], v[20:21], 0, v[184:185]
	v_lshl_add_u64 v[4:5], v[42:43], 1, v[4:5]
	v_lshlrev_b32_e32 v184, 1, v55
	v_add3_u32 v7, v153, v56, v78
	s_waitcnt lgkmcnt(0)
	flat_store_dwordx4 v[4:5], v[0:3]
	ds_read_b128 v[0:3], v8
	v_lshl_add_u64 v[4:5], v[20:21], 0, v[184:185]
	v_lshl_add_u64 v[4:5], v[44:45], 1, v[4:5]
	v_lshlrev_b32_e32 v184, 1, v57
	v_ashrrev_i32_e32 v49, 31, v48
	s_waitcnt lgkmcnt(0)
	flat_store_dwordx4 v[4:5], v[0:3]
	ds_read_b128 v[0:3], v6
	v_lshl_add_u64 v[4:5], v[20:21], 0, v[184:185]
	v_lshl_add_u64 v[4:5], v[46:47], 1, v[4:5]
	v_lshlrev_b32_e32 v184, 1, v58
	v_add3_u32 v6, v153, v59, v79
	s_waitcnt lgkmcnt(0)
	flat_store_dwordx4 v[4:5], v[0:3]
	ds_read_b128 v[0:3], v7
	v_lshl_add_u64 v[4:5], v[20:21], 0, v[184:185]
	v_lshl_add_u64 v[4:5], v[48:49], 1, v[4:5]
	v_lshlrev_b32_e32 v184, 1, v60
	s_waitcnt lgkmcnt(0)
	flat_store_dwordx4 v[4:5], v[0:3]
	ds_read_b128 v[0:3], v6
	v_lshlrev_b32_e32 v6, 3, v52
	v_lshl_add_u64 v[4:5], v[20:21], 0, v[184:185]
	v_ashrrev_i32_e32 v7, 31, v6
	v_lshl_add_u64 v[4:5], v[6:7], 1, v[4:5]
	s_waitcnt lgkmcnt(0)
	flat_store_dwordx4 v[4:5], v[0:3]
	s_waitcnt lgkmcnt(0)
	s_waitcnt lgkmcnt(0)
	s_barrier
	s_branch .LBB0_355
